# f32 matrix cores (v_mfma_f32_16x16x4_f32) also for the three K=1024 token-0 shadow GEMMs (in-proj, out-proj, MLP-up): 32 weight loads issued together, 8 LDS reads, 4-store partial write-out instead of
# speedup vs baseline: 1.0156x; 1.0016x over previous
; template <int M> DEVI float shx(float v) { return __int_as_float(__builtin_amdgcn_ds_swizzle(__float_as_int(v), (M << 10) | 0x1f)); }
; DEVI float shx32(float v, int lane) { return __int_as_float(__builtin_amdgcn_ds_bpermute((lane ^ 32) << 2, __float_as_int(v))); }
; DEVI void sk_gemm(const float* __restrict__ A, int lda, int K, const float* __restrict__ W, int N, const float* __restrict__ gain,
;                   bool use_rs, float* __restrict__ out, int ldo, int mode, unsigned char* lds, int wv, int bid, int nblk) {
;     ...
; #pragma unroll 2
;       for (int k = 0; k < ks; k += 4) {
;         const float w0 = Wp[(size_t)(k + 0) * N], w1 = Wp[(size_t)(k + 1) * N], w2 = Wp[(size_t)(k + 2) * N], w3 = Wp[(size_t)(k + 3) * N];
; #pragma unroll
;         for (int b = 0; b < 16; ++b) { const float4 a = *(const float4*)(Ap + b * 1024 + k); acc[b] += a.x * w0 + a.y * w1 + a.z * w2 + a.w * w3; }
;       }
;     }
; #pragma unroll
;     for (int b = 0; b < 16; ++b) { float v = acc[b]; v += shx<16>(v); v += shx32(v, lane); if (kq == 0) red[(wave * 16 + b) * 16 + c16] = v; }
;     __syncthreads();
;     if (tid < 256) {
;       const int b = tid >> 4, c = tid & 15; float v = 0.f;
; #pragma unroll
;       for (int w = 0; w < 8; ++w) v += red[(w * 16 + b) * 16 + c];
;       const int nn = grp * 16 + c;
;       if (nn < N) {
;         if (use_rs) v *= rsS[b];
;         float* o = out + (size_t)b * ldo + nn;
;         if (mode == 1) *o += v; else if (mode == 2) { v = fmaxf(v, 0.f); *o = v * v; } else *o = v;
.LBB0_264:
	s_mov_b32 s12, 0xfffe4000
	s_mov_b32 s13, -1
	v_lshl_add_u64 v[18:19], v[12:13], 0, s[12:13]
	s_mov_b64 s[12:13], 0x4000
	global_load_dword v186, v[18:19], off
	v_lshl_add_u64 v[18:19], v[18:19], 0, s[12:13]
	global_load_dword v187, v[18:19], off
	v_lshl_add_u64 v[18:19], v[18:19], 0, s[12:13]
	global_load_dword v188, v[18:19], off
	v_lshl_add_u64 v[18:19], v[18:19], 0, s[12:13]
	global_load_dword v189, v[18:19], off
	v_lshl_add_u64 v[18:19], v[18:19], 0, s[12:13]
	global_load_dword v190, v[18:19], off
	v_lshl_add_u64 v[18:19], v[18:19], 0, s[12:13]
	global_load_dword v191, v[18:19], off
	v_lshl_add_u64 v[18:19], v[18:19], 0, s[12:13]
	global_load_dword v192, v[18:19], off
	v_lshl_add_u64 v[18:19], v[18:19], 0, s[12:13]
	global_load_dword v193, v[18:19], off
	v_lshl_add_u64 v[18:19], v[18:19], 0, s[12:13]
	global_load_dword v194, v[18:19], off
	v_lshl_add_u64 v[18:19], v[18:19], 0, s[12:13]
	global_load_dword v195, v[18:19], off
	v_lshl_add_u64 v[18:19], v[18:19], 0, s[12:13]
	global_load_dword v196, v[18:19], off
	v_lshl_add_u64 v[18:19], v[18:19], 0, s[12:13]
	global_load_dword v197, v[18:19], off
	v_lshl_add_u64 v[18:19], v[18:19], 0, s[12:13]
	global_load_dword v198, v[18:19], off
	v_lshl_add_u64 v[18:19], v[18:19], 0, s[12:13]
	global_load_dword v199, v[18:19], off
	v_lshl_add_u64 v[18:19], v[18:19], 0, s[12:13]
	global_load_dword v200, v[18:19], off
	v_lshl_add_u64 v[18:19], v[18:19], 0, s[12:13]
	global_load_dword v201, v[18:19], off
	v_lshl_add_u64 v[18:19], v[18:19], 0, s[12:13]
	global_load_dword v202, v[18:19], off
	v_lshl_add_u64 v[18:19], v[18:19], 0, s[12:13]
	global_load_dword v203, v[18:19], off
	v_lshl_add_u64 v[18:19], v[18:19], 0, s[12:13]
	global_load_dword v204, v[18:19], off
	v_lshl_add_u64 v[18:19], v[18:19], 0, s[12:13]
	global_load_dword v205, v[18:19], off
	v_lshl_add_u64 v[18:19], v[18:19], 0, s[12:13]
	global_load_dword v206, v[18:19], off
	v_lshl_add_u64 v[18:19], v[18:19], 0, s[12:13]
	global_load_dword v207, v[18:19], off
	v_lshl_add_u64 v[18:19], v[18:19], 0, s[12:13]
	global_load_dword v208, v[18:19], off
	v_lshl_add_u64 v[18:19], v[18:19], 0, s[12:13]
	global_load_dword v209, v[18:19], off
	v_lshl_add_u64 v[18:19], v[18:19], 0, s[12:13]
	global_load_dword v210, v[18:19], off
	v_lshl_add_u64 v[18:19], v[18:19], 0, s[12:13]
	global_load_dword v211, v[18:19], off
	v_lshl_add_u64 v[18:19], v[18:19], 0, s[12:13]
	global_load_dword v212, v[18:19], off
	v_lshl_add_u64 v[18:19], v[18:19], 0, s[12:13]
	global_load_dword v213, v[18:19], off
	v_lshl_add_u64 v[18:19], v[18:19], 0, s[12:13]
	global_load_dword v214, v[18:19], off
	v_lshl_add_u64 v[18:19], v[18:19], 0, s[12:13]
	global_load_dword v215, v[18:19], off
	v_lshl_add_u64 v[18:19], v[18:19], 0, s[12:13]
	global_load_dword v216, v[18:19], off
	v_lshl_add_u64 v[18:19], v[18:19], 0, s[12:13]
	global_load_dword v217, v[18:19], off
	v_mbcnt_lo_u32_b32 v20, -1, 0
	v_mbcnt_hi_u32_b32 v20, -1, v20
	v_and_b32_e32 v20, 15, v20
	v_lshl_add_u32 v21, v20, 12, v45
	ds_read_b128 v[182:185], v21
	ds_read_b128 v[218:221], v21 offset:16
	s_waitcnt vmcnt(28) lgkmcnt(1)
	v_mfma_f32_16x16x4_f32 v[14:17], v182, v186, v[14:17]
	v_mfma_f32_16x16x4_f32 v[14:17], v183, v187, v[14:17]
	v_mfma_f32_16x16x4_f32 v[14:17], v184, v188, v[14:17]
	v_mfma_f32_16x16x4_f32 v[14:17], v185, v189, v[14:17]
	ds_read_b128 v[182:185], v21 offset:32
	s_waitcnt vmcnt(24) lgkmcnt(1)
	v_mfma_f32_16x16x4_f32 v[14:17], v218, v190, v[14:17]
	v_mfma_f32_16x16x4_f32 v[14:17], v219, v191, v[14:17]
	v_mfma_f32_16x16x4_f32 v[14:17], v220, v192, v[14:17]
	v_mfma_f32_16x16x4_f32 v[14:17], v221, v193, v[14:17]
	ds_read_b128 v[218:221], v21 offset:48
	s_waitcnt vmcnt(20) lgkmcnt(1)
	v_mfma_f32_16x16x4_f32 v[14:17], v182, v194, v[14:17]
	v_mfma_f32_16x16x4_f32 v[14:17], v183, v195, v[14:17]
	v_mfma_f32_16x16x4_f32 v[14:17], v184, v196, v[14:17]
	v_mfma_f32_16x16x4_f32 v[14:17], v185, v197, v[14:17]
	ds_read_b128 v[182:185], v21 offset:64
	s_waitcnt vmcnt(16) lgkmcnt(1)
	v_mfma_f32_16x16x4_f32 v[14:17], v218, v198, v[14:17]
	v_mfma_f32_16x16x4_f32 v[14:17], v219, v199, v[14:17]
	v_mfma_f32_16x16x4_f32 v[14:17], v220, v200, v[14:17]
	v_mfma_f32_16x16x4_f32 v[14:17], v221, v201, v[14:17]
	ds_read_b128 v[218:221], v21 offset:80
	s_waitcnt vmcnt(12) lgkmcnt(1)
	v_mfma_f32_16x16x4_f32 v[14:17], v182, v202, v[14:17]
	v_mfma_f32_16x16x4_f32 v[14:17], v183, v203, v[14:17]
	v_mfma_f32_16x16x4_f32 v[14:17], v184, v204, v[14:17]
	v_mfma_f32_16x16x4_f32 v[14:17], v185, v205, v[14:17]
	ds_read_b128 v[182:185], v21 offset:96
	s_waitcnt vmcnt(8) lgkmcnt(1)
	v_mfma_f32_16x16x4_f32 v[14:17], v218, v206, v[14:17]
	v_mfma_f32_16x16x4_f32 v[14:17], v219, v207, v[14:17]
	v_mfma_f32_16x16x4_f32 v[14:17], v220, v208, v[14:17]
	v_mfma_f32_16x16x4_f32 v[14:17], v221, v209, v[14:17]
	ds_read_b128 v[218:221], v21 offset:112
	s_waitcnt vmcnt(4) lgkmcnt(1)
	v_mfma_f32_16x16x4_f32 v[14:17], v182, v210, v[14:17]
	v_mfma_f32_16x16x4_f32 v[14:17], v183, v211, v[14:17]
	v_mfma_f32_16x16x4_f32 v[14:17], v184, v212, v[14:17]
	v_mfma_f32_16x16x4_f32 v[14:17], v185, v213, v[14:17]
	s_waitcnt vmcnt(0) lgkmcnt(0)
	v_mfma_f32_16x16x4_f32 v[14:17], v218, v214, v[14:17]
	v_mfma_f32_16x16x4_f32 v[14:17], v219, v215, v[14:17]
	v_mfma_f32_16x16x4_f32 v[14:17], v220, v216, v[14:17]
	v_mfma_f32_16x16x4_f32 v[14:17], v221, v217, v[14:17]
	s_nop 7
	s_nop 3
	v_mbcnt_lo_u32_b32 v20, -1, 0
	v_mbcnt_hi_u32_b32 v20, -1, v20
	v_lshrrev_b32_e32 v20, 4, v20
	v_lshl_add_u32 v20, v20, 8, v46
	ds_write_b32 v20, v14
	ds_write_b32 v20, v15 offset:64
	ds_write_b32 v20, v16 offset:128
	ds_write_b32 v20, v17 offset:192
	v_lshl_or_b32 v0, s2, 4, v35
	s_movk_i32 s3, 0x1000
	v_cmp_gt_i32_e32 vcc, s3, v0
	s_and_b64 s[14:15], s[6:7], vcc
	s_waitcnt lgkmcnt(0)
	s_barrier
	s_and_saveexec_b64 s[12:13], s[14:15]
	s_cbranch_execz .LBB0_258
	ds_read2st64_b32 v[2:3], v41 offset1:4
	s_waitcnt lgkmcnt(0)
	v_add_f32_e32 v1, 0, v2
	v_add_f32_e32 v1, v1, v3
	ds_read2st64_b32 v[2:3], v41 offset0:8 offset1:12
	s_waitcnt lgkmcnt(0)
	v_add_f32_e32 v1, v1, v2
	v_add_f32_e32 v1, v1, v3
	ds_read2st64_b32 v[2:3], v41 offset0:16 offset1:20
	s_waitcnt lgkmcnt(0)
	v_add_f32_e32 v1, v1, v2
	v_add_f32_e32 v1, v1, v3
	ds_read2st64_b32 v[2:3], v41 offset0:24 offset1:28
	s_waitcnt lgkmcnt(0)
	v_add_f32_e32 v1, v1, v2
	ds_read_b32 v2, v42
	v_add_f32_e32 v1, v1, v3
	s_waitcnt lgkmcnt(0)
	v_mul_f32_e32 v2, v1, v2
	v_ashrrev_i32_e32 v1, 31, v0
	v_max_f32_e32 v2, 0, v2
	v_lshl_add_u64 v[0:1], v[0:1], 2, v[4:5]
	v_mul_f32_e32 v2, v2, v2
	global_store_dword v[0:1], v2, off
	s_branch .LBB0_258

; template <int M> DEVI float shx(float v) { return __int_as_float(__builtin_amdgcn_ds_swizzle(__float_as_int(v), (M << 10) | 0x1f)); }
; DEVI float shx32(float v, int lane) { return __int_as_float(__builtin_amdgcn_ds_bpermute((lane ^ 32) << 2, __float_as_int(v))); }
; DEVI void sk_gemm(const float* __restrict__ A, int lda, int K, const float* __restrict__ W, int N, const float* __restrict__ gain,
;                   bool use_rs, float* __restrict__ out, int ldo, int mode, unsigned char* lds, int wv, int bid, int nblk) {
;     ...
; #pragma unroll 2
;       for (int k = 0; k < ks; k += 4) {
;         const float w0 = Wp[(size_t)(k + 0) * N], w1 = Wp[(size_t)(k + 1) * N], w2 = Wp[(size_t)(k + 2) * N], w3 = Wp[(size_t)(k + 3) * N];
; #pragma unroll
;         for (int b = 0; b < 16; ++b) { const float4 a = *(const float4*)(Ap + b * 1024 + k); acc[b] += a.x * w0 + a.y * w1 + a.z * w2 + a.w * w3; }
;       }
;     }
; #pragma unroll
;     for (int b = 0; b < 16; ++b) { float v = acc[b]; v += shx<16>(v); v += shx32(v, lane); if (kq == 0) red[(wave * 16 + b) * 16 + c16] = v; }
;     __syncthreads();
;     if (tid < 256) {
;       const int b = tid >> 4, c = tid & 15; float v = 0.f;
; #pragma unroll
;       for (int w = 0; w < 8; ++w) v += red[(w * 16 + b) * 16 + c];
;       const int nn = grp * 16 + c;
;       if (nn < N) {
;         if (use_rs) v *= rsS[b];
;         float* o = out + (size_t)b * ldo + nn;
;         if (mode == 1) *o += v; else if (mode == 2) { v = fmaxf(v, 0.f); *o = v * v; } else *o = v;
.LBB0_306:
	s_mov_b32 s10, 0xffff9000
	s_mov_b32 s11, -1
	v_lshl_add_u64 v[152:153], v[146:147], 0, s[10:11]
	s_mov_b64 s[10:11], 0x1000
	global_load_dword v186, v[152:153], off
	v_lshl_add_u64 v[152:153], v[152:153], 0, s[10:11]
	global_load_dword v187, v[152:153], off
	v_lshl_add_u64 v[152:153], v[152:153], 0, s[10:11]
	global_load_dword v188, v[152:153], off
	v_lshl_add_u64 v[152:153], v[152:153], 0, s[10:11]
	global_load_dword v189, v[152:153], off
	v_lshl_add_u64 v[152:153], v[152:153], 0, s[10:11]
	global_load_dword v190, v[152:153], off
	v_lshl_add_u64 v[152:153], v[152:153], 0, s[10:11]
	global_load_dword v191, v[152:153], off
	v_lshl_add_u64 v[152:153], v[152:153], 0, s[10:11]
	global_load_dword v192, v[152:153], off
	v_lshl_add_u64 v[152:153], v[152:153], 0, s[10:11]
	global_load_dword v193, v[152:153], off
	v_lshl_add_u64 v[152:153], v[152:153], 0, s[10:11]
	global_load_dword v194, v[152:153], off
	v_lshl_add_u64 v[152:153], v[152:153], 0, s[10:11]
	global_load_dword v195, v[152:153], off
	v_lshl_add_u64 v[152:153], v[152:153], 0, s[10:11]
	global_load_dword v196, v[152:153], off
	v_lshl_add_u64 v[152:153], v[152:153], 0, s[10:11]
	global_load_dword v197, v[152:153], off
	v_lshl_add_u64 v[152:153], v[152:153], 0, s[10:11]
	global_load_dword v198, v[152:153], off
	v_lshl_add_u64 v[152:153], v[152:153], 0, s[10:11]
	global_load_dword v199, v[152:153], off
	v_lshl_add_u64 v[152:153], v[152:153], 0, s[10:11]
	global_load_dword v200, v[152:153], off
	v_lshl_add_u64 v[152:153], v[152:153], 0, s[10:11]
	global_load_dword v201, v[152:153], off
	v_lshl_add_u64 v[152:153], v[152:153], 0, s[10:11]
	global_load_dword v202, v[152:153], off
	v_lshl_add_u64 v[152:153], v[152:153], 0, s[10:11]
	global_load_dword v203, v[152:153], off
	v_lshl_add_u64 v[152:153], v[152:153], 0, s[10:11]
	global_load_dword v204, v[152:153], off
	v_lshl_add_u64 v[152:153], v[152:153], 0, s[10:11]
	global_load_dword v205, v[152:153], off
	v_lshl_add_u64 v[152:153], v[152:153], 0, s[10:11]
	global_load_dword v206, v[152:153], off
	v_lshl_add_u64 v[152:153], v[152:153], 0, s[10:11]
	global_load_dword v207, v[152:153], off
	v_lshl_add_u64 v[152:153], v[152:153], 0, s[10:11]
	global_load_dword v208, v[152:153], off
	v_lshl_add_u64 v[152:153], v[152:153], 0, s[10:11]
	global_load_dword v209, v[152:153], off
	v_lshl_add_u64 v[152:153], v[152:153], 0, s[10:11]
	global_load_dword v210, v[152:153], off
	v_lshl_add_u64 v[152:153], v[152:153], 0, s[10:11]
	global_load_dword v211, v[152:153], off
	v_lshl_add_u64 v[152:153], v[152:153], 0, s[10:11]
	global_load_dword v212, v[152:153], off
	v_lshl_add_u64 v[152:153], v[152:153], 0, s[10:11]
	global_load_dword v213, v[152:153], off
	v_lshl_add_u64 v[152:153], v[152:153], 0, s[10:11]
	global_load_dword v214, v[152:153], off
	v_lshl_add_u64 v[152:153], v[152:153], 0, s[10:11]
	global_load_dword v215, v[152:153], off
	v_lshl_add_u64 v[152:153], v[152:153], 0, s[10:11]
	global_load_dword v216, v[152:153], off
	v_lshl_add_u64 v[152:153], v[152:153], 0, s[10:11]
	global_load_dword v217, v[152:153], off
	v_mbcnt_lo_u32_b32 v154, -1, 0
	v_mbcnt_hi_u32_b32 v154, -1, v154
	v_and_b32_e32 v154, 15, v154
	v_lshl_add_u32 v155, v154, 12, v173
	ds_read_b128 v[182:185], v155
	ds_read_b128 v[218:221], v155 offset:16
	s_waitcnt vmcnt(28) lgkmcnt(1)
	v_mfma_f32_16x16x4_f32 v[148:151], v182, v186, v[148:151]
	v_mfma_f32_16x16x4_f32 v[148:151], v183, v187, v[148:151]
	v_mfma_f32_16x16x4_f32 v[148:151], v184, v188, v[148:151]
	v_mfma_f32_16x16x4_f32 v[148:151], v185, v189, v[148:151]
	ds_read_b128 v[182:185], v155 offset:32
	s_waitcnt vmcnt(24) lgkmcnt(1)
	v_mfma_f32_16x16x4_f32 v[148:151], v218, v190, v[148:151]
	v_mfma_f32_16x16x4_f32 v[148:151], v219, v191, v[148:151]
	v_mfma_f32_16x16x4_f32 v[148:151], v220, v192, v[148:151]
	v_mfma_f32_16x16x4_f32 v[148:151], v221, v193, v[148:151]
	ds_read_b128 v[218:221], v155 offset:48
	s_waitcnt vmcnt(20) lgkmcnt(1)
	v_mfma_f32_16x16x4_f32 v[148:151], v182, v194, v[148:151]
	v_mfma_f32_16x16x4_f32 v[148:151], v183, v195, v[148:151]
	v_mfma_f32_16x16x4_f32 v[148:151], v184, v196, v[148:151]
	v_mfma_f32_16x16x4_f32 v[148:151], v185, v197, v[148:151]
	ds_read_b128 v[182:185], v155 offset:64
	s_waitcnt vmcnt(16) lgkmcnt(1)
	v_mfma_f32_16x16x4_f32 v[148:151], v218, v198, v[148:151]
	v_mfma_f32_16x16x4_f32 v[148:151], v219, v199, v[148:151]
	v_mfma_f32_16x16x4_f32 v[148:151], v220, v200, v[148:151]
	v_mfma_f32_16x16x4_f32 v[148:151], v221, v201, v[148:151]
	ds_read_b128 v[218:221], v155 offset:80
	s_waitcnt vmcnt(12) lgkmcnt(1)
	v_mfma_f32_16x16x4_f32 v[148:151], v182, v202, v[148:151]
	v_mfma_f32_16x16x4_f32 v[148:151], v183, v203, v[148:151]
	v_mfma_f32_16x16x4_f32 v[148:151], v184, v204, v[148:151]
	v_mfma_f32_16x16x4_f32 v[148:151], v185, v205, v[148:151]
	ds_read_b128 v[182:185], v155 offset:96
	s_waitcnt vmcnt(8) lgkmcnt(1)
	v_mfma_f32_16x16x4_f32 v[148:151], v218, v206, v[148:151]
	v_mfma_f32_16x16x4_f32 v[148:151], v219, v207, v[148:151]
	v_mfma_f32_16x16x4_f32 v[148:151], v220, v208, v[148:151]
	v_mfma_f32_16x16x4_f32 v[148:151], v221, v209, v[148:151]
	ds_read_b128 v[218:221], v155 offset:112
	s_waitcnt vmcnt(4) lgkmcnt(1)
	v_mfma_f32_16x16x4_f32 v[148:151], v182, v210, v[148:151]
	v_mfma_f32_16x16x4_f32 v[148:151], v183, v211, v[148:151]
	v_mfma_f32_16x16x4_f32 v[148:151], v184, v212, v[148:151]
	v_mfma_f32_16x16x4_f32 v[148:151], v185, v213, v[148:151]
	s_waitcnt vmcnt(0) lgkmcnt(0)
	v_mfma_f32_16x16x4_f32 v[148:151], v218, v214, v[148:151]
	v_mfma_f32_16x16x4_f32 v[148:151], v219, v215, v[148:151]
	v_mfma_f32_16x16x4_f32 v[148:151], v220, v216, v[148:151]
	v_mfma_f32_16x16x4_f32 v[148:151], v221, v217, v[148:151]
	s_nop 7
	s_nop 3
	v_mbcnt_lo_u32_b32 v154, -1, 0
	v_mbcnt_hi_u32_b32 v154, -1, v154
	v_lshrrev_b32_e32 v154, 4, v154
	v_lshl_add_u32 v154, v154, 8, v172
	ds_write_b32 v154, v148
	ds_write_b32 v154, v149 offset:64
	ds_write_b32 v154, v150 offset:128
	ds_write_b32 v154, v151 offset:192
	v_lshl_or_b32 v0, s2, 4, v131
	s_movk_i32 s3, 0x400
	v_cmp_gt_i32_e64 s[4:5], s3, v0
	s_and_b64 s[10:11], s[0:1], s[4:5]
	s_waitcnt lgkmcnt(0)
	s_barrier
	s_and_saveexec_b64 s[4:5], s[10:11]
	s_cbranch_execz .LBB0_304
	ds_read2st64_b32 v[2:3], v170 offset1:4
	v_ashrrev_i32_e32 v1, 31, v0
	v_lshl_add_u64 v[0:1], v[0:1], 2, v[4:5]
	s_waitcnt lgkmcnt(0)
	v_add_f32_e32 v2, 0, v2
	v_add_f32_e32 v32, v2, v3
	ds_read2st64_b32 v[2:3], v170 offset0:8 offset1:12
	s_waitcnt lgkmcnt(0)
	v_add_f32_e32 v2, v32, v2
	v_add_f32_e32 v32, v2, v3
	ds_read2st64_b32 v[2:3], v170 offset0:16 offset1:20
	s_waitcnt lgkmcnt(0)
	v_add_f32_e32 v2, v32, v2
	v_add_f32_e32 v32, v2, v3
	ds_read2st64_b32 v[2:3], v170 offset0:24 offset1:28
	s_waitcnt lgkmcnt(0)
	v_add_f32_e32 v2, v32, v2
	v_add_f32_e32 v2, v2, v3
	global_load_dword v3, v[0:1], off
	s_waitcnt vmcnt(0)
	v_add_f32_e32 v2, v2, v3
	global_store_dword v[0:1], v2, off
	s_branch .LBB0_304

; template <int M> DEVI float shx(float v) { return __int_as_float(__builtin_amdgcn_ds_swizzle(__float_as_int(v), (M << 10) | 0x1f)); }
; DEVI float shx32(float v, int lane) { return __int_as_float(__builtin_amdgcn_ds_bpermute((lane ^ 32) << 2, __float_as_int(v))); }
; DEVI void sk_gemm(const float* __restrict__ A, int lda, int K, const float* __restrict__ W, int N, const float* __restrict__ gain,
;                   bool use_rs, float* __restrict__ out, int ldo, int mode, unsigned char* lds, int wv, int bid, int nblk) {
;     ...
; #pragma unroll 2
;       for (int k = 0; k < ks; k += 4) {
;         const float w0 = Wp[(size_t)(k + 0) * N], w1 = Wp[(size_t)(k + 1) * N], w2 = Wp[(size_t)(k + 2) * N], w3 = Wp[(size_t)(k + 3) * N];
; #pragma unroll
;         for (int b = 0; b < 16; ++b) { const float4 a = *(const float4*)(Ap + b * 1024 + k); acc[b] += a.x * w0 + a.y * w1 + a.z * w2 + a.w * w3; }
;       }
;     }
; #pragma unroll
;     for (int b = 0; b < 16; ++b) { float v = acc[b]; v += shx<16>(v); v += shx32(v, lane); if (kq == 0) red[(wave * 16 + b) * 16 + c16] = v; }
;     __syncthreads();
;     if (tid < 256) {
;       const int b = tid >> 4, c = tid & 15; float v = 0.f;
; #pragma unroll
;       for (int w = 0; w < 8; ++w) v += red[(w * 16 + b) * 16 + c];
;       const int nn = grp * 16 + c;
;       if (nn < N) {
;         if (use_rs) v *= rsS[b];
;         float* o = out + (size_t)b * ldo + nn;
;         if (mode == 1) *o += v; else if (mode == 2) { v = fmaxf(v, 0.f); *o = v * v; } else *o = v;
.LBB0_426:
	s_mov_b32 s10, 0xfffec688
	s_mov_b32 s11, -1
	v_lshl_add_u64 v[18:19], v[12:13], 0, s[10:11]
	s_mov_b64 s[10:11], 0x2cc8
	global_load_dword v186, v[18:19], off
	v_lshl_add_u64 v[18:19], v[18:19], 0, s[10:11]
	global_load_dword v187, v[18:19], off
	v_lshl_add_u64 v[18:19], v[18:19], 0, s[10:11]
	global_load_dword v188, v[18:19], off
	v_lshl_add_u64 v[18:19], v[18:19], 0, s[10:11]
	global_load_dword v189, v[18:19], off
	v_lshl_add_u64 v[18:19], v[18:19], 0, s[10:11]
	global_load_dword v190, v[18:19], off
	v_lshl_add_u64 v[18:19], v[18:19], 0, s[10:11]
	global_load_dword v191, v[18:19], off
	v_lshl_add_u64 v[18:19], v[18:19], 0, s[10:11]
	global_load_dword v192, v[18:19], off
	v_lshl_add_u64 v[18:19], v[18:19], 0, s[10:11]
	global_load_dword v193, v[18:19], off
	v_lshl_add_u64 v[18:19], v[18:19], 0, s[10:11]
	global_load_dword v194, v[18:19], off
	v_lshl_add_u64 v[18:19], v[18:19], 0, s[10:11]
	global_load_dword v195, v[18:19], off
	v_lshl_add_u64 v[18:19], v[18:19], 0, s[10:11]
	global_load_dword v196, v[18:19], off
	v_lshl_add_u64 v[18:19], v[18:19], 0, s[10:11]
	global_load_dword v197, v[18:19], off
	v_lshl_add_u64 v[18:19], v[18:19], 0, s[10:11]
	global_load_dword v198, v[18:19], off
	v_lshl_add_u64 v[18:19], v[18:19], 0, s[10:11]
	global_load_dword v199, v[18:19], off
	v_lshl_add_u64 v[18:19], v[18:19], 0, s[10:11]
	global_load_dword v200, v[18:19], off
	v_lshl_add_u64 v[18:19], v[18:19], 0, s[10:11]
	global_load_dword v201, v[18:19], off
	v_lshl_add_u64 v[18:19], v[18:19], 0, s[10:11]
	global_load_dword v202, v[18:19], off
	v_lshl_add_u64 v[18:19], v[18:19], 0, s[10:11]
	global_load_dword v203, v[18:19], off
	v_lshl_add_u64 v[18:19], v[18:19], 0, s[10:11]
	global_load_dword v204, v[18:19], off
	v_lshl_add_u64 v[18:19], v[18:19], 0, s[10:11]
	global_load_dword v205, v[18:19], off
	v_lshl_add_u64 v[18:19], v[18:19], 0, s[10:11]
	global_load_dword v206, v[18:19], off
	v_lshl_add_u64 v[18:19], v[18:19], 0, s[10:11]
	global_load_dword v207, v[18:19], off
	v_lshl_add_u64 v[18:19], v[18:19], 0, s[10:11]
	global_load_dword v208, v[18:19], off
	v_lshl_add_u64 v[18:19], v[18:19], 0, s[10:11]
	global_load_dword v209, v[18:19], off
	v_lshl_add_u64 v[18:19], v[18:19], 0, s[10:11]
	global_load_dword v210, v[18:19], off
	v_lshl_add_u64 v[18:19], v[18:19], 0, s[10:11]
	global_load_dword v211, v[18:19], off
	v_lshl_add_u64 v[18:19], v[18:19], 0, s[10:11]
	global_load_dword v212, v[18:19], off
	v_lshl_add_u64 v[18:19], v[18:19], 0, s[10:11]
	global_load_dword v213, v[18:19], off
	v_lshl_add_u64 v[18:19], v[18:19], 0, s[10:11]
	global_load_dword v214, v[18:19], off
	v_lshl_add_u64 v[18:19], v[18:19], 0, s[10:11]
	global_load_dword v215, v[18:19], off
	v_lshl_add_u64 v[18:19], v[18:19], 0, s[10:11]
	global_load_dword v216, v[18:19], off
	v_lshl_add_u64 v[18:19], v[18:19], 0, s[10:11]
	global_load_dword v217, v[18:19], off
	v_mbcnt_lo_u32_b32 v20, -1, 0
	v_mbcnt_hi_u32_b32 v20, -1, v20
	v_and_b32_e32 v20, 15, v20
	v_lshl_add_u32 v21, v20, 12, v45
	ds_read_b128 v[182:185], v21
	ds_read_b128 v[218:221], v21 offset:16
	s_waitcnt vmcnt(28) lgkmcnt(1)
	v_mfma_f32_16x16x4_f32 v[14:17], v182, v186, v[14:17]
	v_mfma_f32_16x16x4_f32 v[14:17], v183, v187, v[14:17]
	v_mfma_f32_16x16x4_f32 v[14:17], v184, v188, v[14:17]
	v_mfma_f32_16x16x4_f32 v[14:17], v185, v189, v[14:17]
	ds_read_b128 v[182:185], v21 offset:32
	s_waitcnt vmcnt(24) lgkmcnt(1)
	v_mfma_f32_16x16x4_f32 v[14:17], v218, v190, v[14:17]
	v_mfma_f32_16x16x4_f32 v[14:17], v219, v191, v[14:17]
	v_mfma_f32_16x16x4_f32 v[14:17], v220, v192, v[14:17]
	v_mfma_f32_16x16x4_f32 v[14:17], v221, v193, v[14:17]
	ds_read_b128 v[218:221], v21 offset:48
	s_waitcnt vmcnt(20) lgkmcnt(1)
	v_mfma_f32_16x16x4_f32 v[14:17], v182, v194, v[14:17]
	v_mfma_f32_16x16x4_f32 v[14:17], v183, v195, v[14:17]
	v_mfma_f32_16x16x4_f32 v[14:17], v184, v196, v[14:17]
	v_mfma_f32_16x16x4_f32 v[14:17], v185, v197, v[14:17]
	ds_read_b128 v[182:185], v21 offset:64
	s_waitcnt vmcnt(16) lgkmcnt(1)
	v_mfma_f32_16x16x4_f32 v[14:17], v218, v198, v[14:17]
	v_mfma_f32_16x16x4_f32 v[14:17], v219, v199, v[14:17]
	v_mfma_f32_16x16x4_f32 v[14:17], v220, v200, v[14:17]
	v_mfma_f32_16x16x4_f32 v[14:17], v221, v201, v[14:17]
	ds_read_b128 v[218:221], v21 offset:80
	s_waitcnt vmcnt(12) lgkmcnt(1)
	v_mfma_f32_16x16x4_f32 v[14:17], v182, v202, v[14:17]
	v_mfma_f32_16x16x4_f32 v[14:17], v183, v203, v[14:17]
	v_mfma_f32_16x16x4_f32 v[14:17], v184, v204, v[14:17]
	v_mfma_f32_16x16x4_f32 v[14:17], v185, v205, v[14:17]
	ds_read_b128 v[182:185], v21 offset:96
	s_waitcnt vmcnt(8) lgkmcnt(1)
	v_mfma_f32_16x16x4_f32 v[14:17], v218, v206, v[14:17]
	v_mfma_f32_16x16x4_f32 v[14:17], v219, v207, v[14:17]
	v_mfma_f32_16x16x4_f32 v[14:17], v220, v208, v[14:17]
	v_mfma_f32_16x16x4_f32 v[14:17], v221, v209, v[14:17]
	ds_read_b128 v[218:221], v21 offset:112
	s_waitcnt vmcnt(4) lgkmcnt(1)
	v_mfma_f32_16x16x4_f32 v[14:17], v182, v210, v[14:17]
	v_mfma_f32_16x16x4_f32 v[14:17], v183, v211, v[14:17]
	v_mfma_f32_16x16x4_f32 v[14:17], v184, v212, v[14:17]
	v_mfma_f32_16x16x4_f32 v[14:17], v185, v213, v[14:17]
	s_waitcnt vmcnt(0) lgkmcnt(0)
	v_mfma_f32_16x16x4_f32 v[14:17], v218, v214, v[14:17]
	v_mfma_f32_16x16x4_f32 v[14:17], v219, v215, v[14:17]
	v_mfma_f32_16x16x4_f32 v[14:17], v220, v216, v[14:17]
	v_mfma_f32_16x16x4_f32 v[14:17], v221, v217, v[14:17]
	s_nop 7
	s_nop 3
	v_mbcnt_lo_u32_b32 v20, -1, 0
	v_mbcnt_hi_u32_b32 v20, -1, v20
	v_lshrrev_b32_e32 v20, 4, v20
	v_lshl_add_u32 v20, v20, 8, v46
	ds_write_b32 v20, v14
	ds_write_b32 v20, v15 offset:64
	ds_write_b32 v20, v16 offset:128
	ds_write_b32 v20, v17 offset:192
	v_lshl_or_b32 v0, s2, 4, v35
	s_movk_i32 s3, 0xb32
	v_cmp_gt_i32_e32 vcc, s3, v0
	s_and_b64 s[12:13], s[6:7], vcc
	s_waitcnt lgkmcnt(0)
	s_barrier
	s_and_saveexec_b64 s[10:11], s[12:13]
	s_cbranch_execz .LBB0_420
	ds_read2st64_b32 v[2:3], v41 offset1:4
	ds_read2st64_b32 v[12:13], v41 offset0:8 offset1:12
	ds_read2st64_b32 v[14:15], v41 offset0:16 offset1:20
	v_ashrrev_i32_e32 v1, 31, v0
	v_lshl_add_u64 v[0:1], v[0:1], 2, v[4:5]
	s_waitcnt lgkmcnt(2)
	v_add_f32_e32 v2, 0, v2
	v_add_f32_e32 v2, v2, v3
	s_waitcnt lgkmcnt(1)
	v_add_f32_e32 v11, v2, v12
	ds_read2st64_b32 v[2:3], v41 offset0:24 offset1:28
	v_add_f32_e32 v11, v11, v13
	ds_read_b32 v12, v42
	s_waitcnt lgkmcnt(2)
	v_add_f32_e32 v11, v11, v14
	v_add_f32_e32 v11, v11, v15
	s_waitcnt lgkmcnt(1)
	v_add_f32_e32 v2, v11, v2
	v_add_f32_e32 v2, v2, v3
	s_waitcnt lgkmcnt(0)
	v_mul_f32_e32 v2, v2, v12
	global_store_dword v[0:1], v2, off
	s_branch .LBB0_420

; template <int M> DEVI float shx(float v) { return __int_as_float(__builtin_amdgcn_ds_swizzle(__float_as_int(v), (M << 10) | 0x1f)); }
; DEVI float shx32(float v, int lane) { return __int_as_float(__builtin_amdgcn_ds_bpermute((lane ^ 32) << 2, __float_as_int(v))); }
; DEVI void sk_gemm(const float* __restrict__ A, int lda, int K, const float* __restrict__ W, int N, const float* __restrict__ gain,
;                   bool use_rs, float* __restrict__ out, int ldo, int mode, unsigned char* lds, int wv, int bid, int nblk) {
;     ...
; #pragma unroll 2
;       for (int k = 0; k < ks; k += 4) {
;         const float w0 = Wp[(size_t)(k + 0) * N], w1 = Wp[(size_t)(k + 1) * N], w2 = Wp[(size_t)(k + 2) * N], w3 = Wp[(size_t)(k + 3) * N];
; #pragma unroll
;         for (int b = 0; b < 16; ++b) { const float4 a = *(const float4*)(Ap + b * 1024 + k); acc[b] += a.x * w0 + a.y * w1 + a.z * w2 + a.w * w3; }
;       }
;     }
; #pragma unroll
;     for (int b = 0; b < 16; ++b) { float v = acc[b]; v += shx<16>(v); v += shx32(v, lane); if (kq == 0) red[(wave * 16 + b) * 16 + c16] = v; }
;     __syncthreads();
;     if (tid < 256) {
;       const int b = tid >> 4, c = tid & 15; float v = 0.f;
; #pragma unroll
;       for (int w = 0; w < 8; ++w) v += red[(w * 16 + b) * 16 + c];
;       const int nn = grp * 16 + c;
;       if (nn < N) {
;         if (use_rs) v *= rsS[b];
;         float* o = out + (size_t)b * ldo + nn;
;         if (mode == 1) *o += v; else if (mode == 2) { v = fmaxf(v, 0.f); *o = v * v; } else *o = v;
.LBB0_680:
	s_mov_b32 s10, 0xffff9000
	s_mov_b32 s11, -1
	v_lshl_add_u64 v[152:153], v[146:147], 0, s[10:11]
	s_mov_b64 s[10:11], 0x1000
	global_load_dword v186, v[152:153], off
	v_lshl_add_u64 v[152:153], v[152:153], 0, s[10:11]
	global_load_dword v187, v[152:153], off
	v_lshl_add_u64 v[152:153], v[152:153], 0, s[10:11]
	global_load_dword v188, v[152:153], off
	v_lshl_add_u64 v[152:153], v[152:153], 0, s[10:11]
	global_load_dword v189, v[152:153], off
	v_lshl_add_u64 v[152:153], v[152:153], 0, s[10:11]
	global_load_dword v190, v[152:153], off
	v_lshl_add_u64 v[152:153], v[152:153], 0, s[10:11]
	global_load_dword v191, v[152:153], off
	v_lshl_add_u64 v[152:153], v[152:153], 0, s[10:11]
	global_load_dword v192, v[152:153], off
	v_lshl_add_u64 v[152:153], v[152:153], 0, s[10:11]
	global_load_dword v193, v[152:153], off
	v_lshl_add_u64 v[152:153], v[152:153], 0, s[10:11]
	global_load_dword v194, v[152:153], off
	v_lshl_add_u64 v[152:153], v[152:153], 0, s[10:11]
	global_load_dword v195, v[152:153], off
	v_lshl_add_u64 v[152:153], v[152:153], 0, s[10:11]
	global_load_dword v196, v[152:153], off
	v_lshl_add_u64 v[152:153], v[152:153], 0, s[10:11]
	global_load_dword v197, v[152:153], off
	v_lshl_add_u64 v[152:153], v[152:153], 0, s[10:11]
	global_load_dword v198, v[152:153], off
	v_lshl_add_u64 v[152:153], v[152:153], 0, s[10:11]
	global_load_dword v199, v[152:153], off
	v_lshl_add_u64 v[152:153], v[152:153], 0, s[10:11]
	global_load_dword v200, v[152:153], off
	v_lshl_add_u64 v[152:153], v[152:153], 0, s[10:11]
	global_load_dword v201, v[152:153], off
	v_lshl_add_u64 v[152:153], v[152:153], 0, s[10:11]
	global_load_dword v202, v[152:153], off
	v_lshl_add_u64 v[152:153], v[152:153], 0, s[10:11]
	global_load_dword v203, v[152:153], off
	v_lshl_add_u64 v[152:153], v[152:153], 0, s[10:11]
	global_load_dword v204, v[152:153], off
	v_lshl_add_u64 v[152:153], v[152:153], 0, s[10:11]
	global_load_dword v205, v[152:153], off
	v_lshl_add_u64 v[152:153], v[152:153], 0, s[10:11]
	global_load_dword v206, v[152:153], off
	v_lshl_add_u64 v[152:153], v[152:153], 0, s[10:11]
	global_load_dword v207, v[152:153], off
	v_lshl_add_u64 v[152:153], v[152:153], 0, s[10:11]
	global_load_dword v208, v[152:153], off
	v_lshl_add_u64 v[152:153], v[152:153], 0, s[10:11]
	global_load_dword v209, v[152:153], off
	v_lshl_add_u64 v[152:153], v[152:153], 0, s[10:11]
	global_load_dword v210, v[152:153], off
	v_lshl_add_u64 v[152:153], v[152:153], 0, s[10:11]
	global_load_dword v211, v[152:153], off
	v_lshl_add_u64 v[152:153], v[152:153], 0, s[10:11]
	global_load_dword v212, v[152:153], off
	v_lshl_add_u64 v[152:153], v[152:153], 0, s[10:11]
	global_load_dword v213, v[152:153], off
	v_lshl_add_u64 v[152:153], v[152:153], 0, s[10:11]
	global_load_dword v214, v[152:153], off
	v_lshl_add_u64 v[152:153], v[152:153], 0, s[10:11]
	global_load_dword v215, v[152:153], off
	v_lshl_add_u64 v[152:153], v[152:153], 0, s[10:11]
	global_load_dword v216, v[152:153], off
	v_lshl_add_u64 v[152:153], v[152:153], 0, s[10:11]
	global_load_dword v217, v[152:153], off
	v_mbcnt_lo_u32_b32 v154, -1, 0
	v_mbcnt_hi_u32_b32 v154, -1, v154
	v_and_b32_e32 v154, 15, v154
	v_lshl_add_u32 v155, v154, 12, v172
	ds_read_b128 v[182:185], v155
	ds_read_b128 v[218:221], v155 offset:16
	s_waitcnt vmcnt(28) lgkmcnt(1)
	v_mfma_f32_16x16x4_f32 v[148:151], v182, v186, v[148:151]
	v_mfma_f32_16x16x4_f32 v[148:151], v183, v187, v[148:151]
	v_mfma_f32_16x16x4_f32 v[148:151], v184, v188, v[148:151]
	v_mfma_f32_16x16x4_f32 v[148:151], v185, v189, v[148:151]
	ds_read_b128 v[182:185], v155 offset:32
	s_waitcnt vmcnt(24) lgkmcnt(1)
	v_mfma_f32_16x16x4_f32 v[148:151], v218, v190, v[148:151]
	v_mfma_f32_16x16x4_f32 v[148:151], v219, v191, v[148:151]
	v_mfma_f32_16x16x4_f32 v[148:151], v220, v192, v[148:151]
	v_mfma_f32_16x16x4_f32 v[148:151], v221, v193, v[148:151]
	ds_read_b128 v[218:221], v155 offset:48
	s_waitcnt vmcnt(20) lgkmcnt(1)
	v_mfma_f32_16x16x4_f32 v[148:151], v182, v194, v[148:151]
	v_mfma_f32_16x16x4_f32 v[148:151], v183, v195, v[148:151]
	v_mfma_f32_16x16x4_f32 v[148:151], v184, v196, v[148:151]
	v_mfma_f32_16x16x4_f32 v[148:151], v185, v197, v[148:151]
	ds_read_b128 v[182:185], v155 offset:64
	s_waitcnt vmcnt(16) lgkmcnt(1)
	v_mfma_f32_16x16x4_f32 v[148:151], v218, v198, v[148:151]
	v_mfma_f32_16x16x4_f32 v[148:151], v219, v199, v[148:151]
	v_mfma_f32_16x16x4_f32 v[148:151], v220, v200, v[148:151]
	v_mfma_f32_16x16x4_f32 v[148:151], v221, v201, v[148:151]
	ds_read_b128 v[218:221], v155 offset:80
	s_waitcnt vmcnt(12) lgkmcnt(1)
	v_mfma_f32_16x16x4_f32 v[148:151], v182, v202, v[148:151]
	v_mfma_f32_16x16x4_f32 v[148:151], v183, v203, v[148:151]
	v_mfma_f32_16x16x4_f32 v[148:151], v184, v204, v[148:151]
	v_mfma_f32_16x16x4_f32 v[148:151], v185, v205, v[148:151]
	ds_read_b128 v[182:185], v155 offset:96
	s_waitcnt vmcnt(8) lgkmcnt(1)
	v_mfma_f32_16x16x4_f32 v[148:151], v218, v206, v[148:151]
	v_mfma_f32_16x16x4_f32 v[148:151], v219, v207, v[148:151]
	v_mfma_f32_16x16x4_f32 v[148:151], v220, v208, v[148:151]
	v_mfma_f32_16x16x4_f32 v[148:151], v221, v209, v[148:151]
	ds_read_b128 v[218:221], v155 offset:112
	s_waitcnt vmcnt(4) lgkmcnt(1)
	v_mfma_f32_16x16x4_f32 v[148:151], v182, v210, v[148:151]
	v_mfma_f32_16x16x4_f32 v[148:151], v183, v211, v[148:151]
	v_mfma_f32_16x16x4_f32 v[148:151], v184, v212, v[148:151]
	v_mfma_f32_16x16x4_f32 v[148:151], v185, v213, v[148:151]
	s_waitcnt vmcnt(0) lgkmcnt(0)
	v_mfma_f32_16x16x4_f32 v[148:151], v218, v214, v[148:151]
	v_mfma_f32_16x16x4_f32 v[148:151], v219, v215, v[148:151]
	v_mfma_f32_16x16x4_f32 v[148:151], v220, v216, v[148:151]
	v_mfma_f32_16x16x4_f32 v[148:151], v221, v217, v[148:151]
	s_nop 7
	s_nop 3
	v_mbcnt_lo_u32_b32 v154, -1, 0
	v_mbcnt_hi_u32_b32 v154, -1, v154
	v_lshrrev_b32_e32 v154, 4, v154
	v_lshl_add_u32 v154, v154, 8, v173
	ds_write_b32 v154, v148
	ds_write_b32 v154, v149 offset:64
	ds_write_b32 v154, v150 offset:128
	ds_write_b32 v154, v151 offset:192
	v_lshl_or_b32 v0, s2, 4, v131
	s_movk_i32 s3, 0x400
	v_cmp_gt_i32_e64 s[4:5], s3, v0
	s_and_b64 s[10:11], s[0:1], s[4:5]
	s_waitcnt lgkmcnt(0)
	s_barrier
	s_and_saveexec_b64 s[4:5], s[10:11]
	s_cbranch_execz .LBB0_678
	ds_read2st64_b32 v[2:3], v170 offset1:4
	v_ashrrev_i32_e32 v1, 31, v0
	v_lshl_add_u64 v[0:1], v[0:1], 2, v[4:5]
	s_waitcnt lgkmcnt(0)
	v_add_f32_e32 v2, 0, v2
	v_add_f32_e32 v32, v2, v3
	ds_read2st64_b32 v[2:3], v170 offset0:8 offset1:12
	s_waitcnt lgkmcnt(0)
	v_add_f32_e32 v2, v32, v2
	v_add_f32_e32 v32, v2, v3
	ds_read2st64_b32 v[2:3], v170 offset0:16 offset1:20
	s_waitcnt lgkmcnt(0)
	v_add_f32_e32 v2, v32, v2
	v_add_f32_e32 v32, v2, v3
	ds_read2st64_b32 v[2:3], v170 offset0:24 offset1:28
	s_waitcnt lgkmcnt(0)
	v_add_f32_e32 v2, v32, v2
	v_add_f32_e32 v2, v2, v3
	global_load_dword v3, v[0:1], off
	s_waitcnt vmcnt(0)
	v_add_f32_e32 v2, v2, v3
	global_store_dword v[0:1], v2, off
	s_branch .LBB0_678

; template <int M> DEVI float shx(float v) { return __int_as_float(__builtin_amdgcn_ds_swizzle(__float_as_int(v), (M << 10) | 0x1f)); }
; DEVI float shx32(float v, int lane) { return __int_as_float(__builtin_amdgcn_ds_bpermute((lane ^ 32) << 2, __float_as_int(v))); }
; DEVI void sk_gemm(const float* __restrict__ A, int lda, int K, const float* __restrict__ W, int N, const float* __restrict__ gain,
;                   bool use_rs, float* __restrict__ out, int ldo, int mode, unsigned char* lds, int wv, int bid, int nblk) {
;     ...
; #pragma unroll 2
;       for (int k = 0; k < ks; k += 4) {
;         const float w0 = Wp[(size_t)(k + 0) * N], w1 = Wp[(size_t)(k + 1) * N], w2 = Wp[(size_t)(k + 2) * N], w3 = Wp[(size_t)(k + 3) * N];
; #pragma unroll
;         for (int b = 0; b < 16; ++b) { const float4 a = *(const float4*)(Ap + b * 1024 + k); acc[b] += a.x * w0 + a.y * w1 + a.z * w2 + a.w * w3; }
;       }
;     }
; #pragma unroll
;     for (int b = 0; b < 16; ++b) { float v = acc[b]; v += shx<16>(v); v += shx32(v, lane); if (kq == 0) red[(wave * 16 + b) * 16 + c16] = v; }
;     __syncthreads();
;     if (tid < 256) {
;       const int b = tid >> 4, c = tid & 15; float v = 0.f;
; #pragma unroll
;       for (int w = 0; w < 8; ++w) v += red[(w * 16 + b) * 16 + c];
;       const int nn = grp * 16 + c;
;       if (nn < N) {
;         if (use_rs) v *= rsS[b];
;         float* o = out + (size_t)b * ldo + nn;
;         if (mode == 1) *o += v; else if (mode == 2) { v = fmaxf(v, 0.f); *o = v * v; } else *o = v;
.LBB0_795:
	s_mov_b32 s10, 0xfffec688
	s_mov_b32 s11, -1
	v_lshl_add_u64 v[18:19], v[12:13], 0, s[10:11]
	s_mov_b64 s[10:11], 0x2cc8
	global_load_dword v186, v[18:19], off
	v_lshl_add_u64 v[18:19], v[18:19], 0, s[10:11]
	global_load_dword v187, v[18:19], off
	v_lshl_add_u64 v[18:19], v[18:19], 0, s[10:11]
	global_load_dword v188, v[18:19], off
	v_lshl_add_u64 v[18:19], v[18:19], 0, s[10:11]
	global_load_dword v189, v[18:19], off
	v_lshl_add_u64 v[18:19], v[18:19], 0, s[10:11]
	global_load_dword v190, v[18:19], off
	v_lshl_add_u64 v[18:19], v[18:19], 0, s[10:11]
	global_load_dword v191, v[18:19], off
	v_lshl_add_u64 v[18:19], v[18:19], 0, s[10:11]
	global_load_dword v192, v[18:19], off
	v_lshl_add_u64 v[18:19], v[18:19], 0, s[10:11]
	global_load_dword v193, v[18:19], off
	v_lshl_add_u64 v[18:19], v[18:19], 0, s[10:11]
	global_load_dword v194, v[18:19], off
	v_lshl_add_u64 v[18:19], v[18:19], 0, s[10:11]
	global_load_dword v195, v[18:19], off
	v_lshl_add_u64 v[18:19], v[18:19], 0, s[10:11]
	global_load_dword v196, v[18:19], off
	v_lshl_add_u64 v[18:19], v[18:19], 0, s[10:11]
	global_load_dword v197, v[18:19], off
	v_lshl_add_u64 v[18:19], v[18:19], 0, s[10:11]
	global_load_dword v198, v[18:19], off
	v_lshl_add_u64 v[18:19], v[18:19], 0, s[10:11]
	global_load_dword v199, v[18:19], off
	v_lshl_add_u64 v[18:19], v[18:19], 0, s[10:11]
	global_load_dword v200, v[18:19], off
	v_lshl_add_u64 v[18:19], v[18:19], 0, s[10:11]
	global_load_dword v201, v[18:19], off
	v_lshl_add_u64 v[18:19], v[18:19], 0, s[10:11]
	global_load_dword v202, v[18:19], off
	v_lshl_add_u64 v[18:19], v[18:19], 0, s[10:11]
	global_load_dword v203, v[18:19], off
	v_lshl_add_u64 v[18:19], v[18:19], 0, s[10:11]
	global_load_dword v204, v[18:19], off
	v_lshl_add_u64 v[18:19], v[18:19], 0, s[10:11]
	global_load_dword v205, v[18:19], off
	v_lshl_add_u64 v[18:19], v[18:19], 0, s[10:11]
	global_load_dword v206, v[18:19], off
	v_lshl_add_u64 v[18:19], v[18:19], 0, s[10:11]
	global_load_dword v207, v[18:19], off
	v_lshl_add_u64 v[18:19], v[18:19], 0, s[10:11]
	global_load_dword v208, v[18:19], off
	v_lshl_add_u64 v[18:19], v[18:19], 0, s[10:11]
	global_load_dword v209, v[18:19], off
	v_lshl_add_u64 v[18:19], v[18:19], 0, s[10:11]
	global_load_dword v210, v[18:19], off
	v_lshl_add_u64 v[18:19], v[18:19], 0, s[10:11]
	global_load_dword v211, v[18:19], off
	v_lshl_add_u64 v[18:19], v[18:19], 0, s[10:11]
	global_load_dword v212, v[18:19], off
	v_lshl_add_u64 v[18:19], v[18:19], 0, s[10:11]
	global_load_dword v213, v[18:19], off
	v_lshl_add_u64 v[18:19], v[18:19], 0, s[10:11]
	global_load_dword v214, v[18:19], off
	v_lshl_add_u64 v[18:19], v[18:19], 0, s[10:11]
	global_load_dword v215, v[18:19], off
	v_lshl_add_u64 v[18:19], v[18:19], 0, s[10:11]
	global_load_dword v216, v[18:19], off
	v_lshl_add_u64 v[18:19], v[18:19], 0, s[10:11]
	global_load_dword v217, v[18:19], off
	v_mbcnt_lo_u32_b32 v20, -1, 0
	v_mbcnt_hi_u32_b32 v20, -1, v20
	v_and_b32_e32 v20, 15, v20
	v_lshl_add_u32 v21, v20, 12, v45
	ds_read_b128 v[182:185], v21
	ds_read_b128 v[218:221], v21 offset:16
	s_waitcnt vmcnt(28) lgkmcnt(1)
	v_mfma_f32_16x16x4_f32 v[14:17], v182, v186, v[14:17]
	v_mfma_f32_16x16x4_f32 v[14:17], v183, v187, v[14:17]
	v_mfma_f32_16x16x4_f32 v[14:17], v184, v188, v[14:17]
	v_mfma_f32_16x16x4_f32 v[14:17], v185, v189, v[14:17]
	ds_read_b128 v[182:185], v21 offset:32
	s_waitcnt vmcnt(24) lgkmcnt(1)
	v_mfma_f32_16x16x4_f32 v[14:17], v218, v190, v[14:17]
	v_mfma_f32_16x16x4_f32 v[14:17], v219, v191, v[14:17]
	v_mfma_f32_16x16x4_f32 v[14:17], v220, v192, v[14:17]
	v_mfma_f32_16x16x4_f32 v[14:17], v221, v193, v[14:17]
	ds_read_b128 v[218:221], v21 offset:48
	s_waitcnt vmcnt(20) lgkmcnt(1)
	v_mfma_f32_16x16x4_f32 v[14:17], v182, v194, v[14:17]
	v_mfma_f32_16x16x4_f32 v[14:17], v183, v195, v[14:17]
	v_mfma_f32_16x16x4_f32 v[14:17], v184, v196, v[14:17]
	v_mfma_f32_16x16x4_f32 v[14:17], v185, v197, v[14:17]
	ds_read_b128 v[182:185], v21 offset:64
	s_waitcnt vmcnt(16) lgkmcnt(1)
	v_mfma_f32_16x16x4_f32 v[14:17], v218, v198, v[14:17]
	v_mfma_f32_16x16x4_f32 v[14:17], v219, v199, v[14:17]
	v_mfma_f32_16x16x4_f32 v[14:17], v220, v200, v[14:17]
	v_mfma_f32_16x16x4_f32 v[14:17], v221, v201, v[14:17]
	ds_read_b128 v[218:221], v21 offset:80
	s_waitcnt vmcnt(12) lgkmcnt(1)
	v_mfma_f32_16x16x4_f32 v[14:17], v182, v202, v[14:17]
	v_mfma_f32_16x16x4_f32 v[14:17], v183, v203, v[14:17]
	v_mfma_f32_16x16x4_f32 v[14:17], v184, v204, v[14:17]
	v_mfma_f32_16x16x4_f32 v[14:17], v185, v205, v[14:17]
	ds_read_b128 v[182:185], v21 offset:96
	s_waitcnt vmcnt(8) lgkmcnt(1)
	v_mfma_f32_16x16x4_f32 v[14:17], v218, v206, v[14:17]
	v_mfma_f32_16x16x4_f32 v[14:17], v219, v207, v[14:17]
	v_mfma_f32_16x16x4_f32 v[14:17], v220, v208, v[14:17]
	v_mfma_f32_16x16x4_f32 v[14:17], v221, v209, v[14:17]
	ds_read_b128 v[218:221], v21 offset:112
	s_waitcnt vmcnt(4) lgkmcnt(1)
	v_mfma_f32_16x16x4_f32 v[14:17], v182, v210, v[14:17]
	v_mfma_f32_16x16x4_f32 v[14:17], v183, v211, v[14:17]
	v_mfma_f32_16x16x4_f32 v[14:17], v184, v212, v[14:17]
	v_mfma_f32_16x16x4_f32 v[14:17], v185, v213, v[14:17]
	s_waitcnt vmcnt(0) lgkmcnt(0)
	v_mfma_f32_16x16x4_f32 v[14:17], v218, v214, v[14:17]
	v_mfma_f32_16x16x4_f32 v[14:17], v219, v215, v[14:17]
	v_mfma_f32_16x16x4_f32 v[14:17], v220, v216, v[14:17]
	v_mfma_f32_16x16x4_f32 v[14:17], v221, v217, v[14:17]
	s_nop 7
	s_nop 3
	v_mbcnt_lo_u32_b32 v20, -1, 0
	v_mbcnt_hi_u32_b32 v20, -1, v20
	v_lshrrev_b32_e32 v20, 4, v20
	v_lshl_add_u32 v20, v20, 8, v46
	ds_write_b32 v20, v14
	ds_write_b32 v20, v15 offset:64
	ds_write_b32 v20, v16 offset:128
	ds_write_b32 v20, v17 offset:192
	v_lshl_or_b32 v0, s2, 4, v35
	s_movk_i32 s3, 0xb32
	v_cmp_gt_i32_e32 vcc, s3, v0
	s_and_b64 s[12:13], s[6:7], vcc
	s_waitcnt lgkmcnt(0)
	s_barrier
	s_and_saveexec_b64 s[10:11], s[12:13]
	s_cbranch_execz .LBB0_789
	ds_read2st64_b32 v[2:3], v41 offset1:4
	v_ashrrev_i32_e32 v1, 31, v0
	v_lshl_add_u64 v[0:1], v[0:1], 2, v[4:5]
	s_waitcnt lgkmcnt(0)
	v_add_f32_e32 v2, 0, v2
	v_add_f32_e32 v11, v2, v3
	ds_read2st64_b32 v[2:3], v41 offset0:8 offset1:12
	s_waitcnt lgkmcnt(0)
	v_add_f32_e32 v2, v11, v2
	v_add_f32_e32 v11, v2, v3
	ds_read2st64_b32 v[2:3], v41 offset0:16 offset1:20
	s_waitcnt lgkmcnt(0)
	v_add_f32_e32 v2, v11, v2
	v_add_f32_e32 v11, v2, v3
	ds_read2st64_b32 v[2:3], v41 offset0:24 offset1:28
	s_waitcnt lgkmcnt(0)
	v_add_f32_e32 v2, v11, v2
	v_add_f32_e32 v2, v2, v3
	ds_read_b32 v3, v42
	s_waitcnt lgkmcnt(0)
	v_mul_f32_e32 v2, v2, v3
	global_store_dword v[0:1], v2, off
	s_branch .LBB0_789

; template <int M> DEVI float shx(float v) { return __int_as_float(__builtin_amdgcn_ds_swizzle(__float_as_int(v), (M << 10) | 0x1f)); }
; DEVI float shx32(float v, int lane) { return __int_as_float(__builtin_amdgcn_ds_bpermute((lane ^ 32) << 2, __float_as_int(v))); }
; DEVI void sk_gemm(const float* __restrict__ A, int lda, int K, const float* __restrict__ W, int N, const float* __restrict__ gain,
;                   bool use_rs, float* __restrict__ out, int ldo, int mode, unsigned char* lds, int wv, int bid, int nblk) {
;     ...
; #pragma unroll 2
;       for (int k = 0; k < ks; k += 4) {
;         const float w0 = Wp[(size_t)(k + 0) * N], w1 = Wp[(size_t)(k + 1) * N], w2 = Wp[(size_t)(k + 2) * N], w3 = Wp[(size_t)(k + 3) * N];
; #pragma unroll
;         for (int b = 0; b < 16; ++b) { const float4 a = *(const float4*)(Ap + b * 1024 + k); acc[b] += a.x * w0 + a.y * w1 + a.z * w2 + a.w * w3; }
;       }
;     }
; #pragma unroll
;     for (int b = 0; b < 16; ++b) { float v = acc[b]; v += shx<16>(v); v += shx32(v, lane); if (kq == 0) red[(wave * 16 + b) * 16 + c16] = v; }
;     __syncthreads();
;     if (tid < 256) {
;       const int b = tid >> 4, c = tid & 15; float v = 0.f;
; #pragma unroll
;       for (int w = 0; w < 8; ++w) v += red[(w * 16 + b) * 16 + c];
;       const int nn = grp * 16 + c;
;       if (nn < N) {
;         if (use_rs) v *= rsS[b];
;         float* o = out + (size_t)b * ldo + nn;
;         if (mode == 1) *o += v; else if (mode == 2) { v = fmaxf(v, 0.f); *o = v * v; } else *o = v;
.LBB0_1057:
	s_mov_b32 s14, 0xfffe4000
	s_mov_b32 s15, -1
	v_lshl_add_u64 v[18:19], v[12:13], 0, s[14:15]
	s_mov_b64 s[14:15], 0x4000
	global_load_dword v186, v[18:19], off
	v_lshl_add_u64 v[18:19], v[18:19], 0, s[14:15]
	global_load_dword v187, v[18:19], off
	v_lshl_add_u64 v[18:19], v[18:19], 0, s[14:15]
	global_load_dword v188, v[18:19], off
	v_lshl_add_u64 v[18:19], v[18:19], 0, s[14:15]
	global_load_dword v189, v[18:19], off
	v_lshl_add_u64 v[18:19], v[18:19], 0, s[14:15]
	global_load_dword v190, v[18:19], off
	v_lshl_add_u64 v[18:19], v[18:19], 0, s[14:15]
	global_load_dword v191, v[18:19], off
	v_lshl_add_u64 v[18:19], v[18:19], 0, s[14:15]
	global_load_dword v192, v[18:19], off
	v_lshl_add_u64 v[18:19], v[18:19], 0, s[14:15]
	global_load_dword v193, v[18:19], off
	v_lshl_add_u64 v[18:19], v[18:19], 0, s[14:15]
	global_load_dword v194, v[18:19], off
	v_lshl_add_u64 v[18:19], v[18:19], 0, s[14:15]
	global_load_dword v195, v[18:19], off
	v_lshl_add_u64 v[18:19], v[18:19], 0, s[14:15]
	global_load_dword v196, v[18:19], off
	v_lshl_add_u64 v[18:19], v[18:19], 0, s[14:15]
	global_load_dword v197, v[18:19], off
	v_lshl_add_u64 v[18:19], v[18:19], 0, s[14:15]
	global_load_dword v198, v[18:19], off
	v_lshl_add_u64 v[18:19], v[18:19], 0, s[14:15]
	global_load_dword v199, v[18:19], off
	v_lshl_add_u64 v[18:19], v[18:19], 0, s[14:15]
	global_load_dword v200, v[18:19], off
	v_lshl_add_u64 v[18:19], v[18:19], 0, s[14:15]
	global_load_dword v201, v[18:19], off
	v_lshl_add_u64 v[18:19], v[18:19], 0, s[14:15]
	global_load_dword v202, v[18:19], off
	v_lshl_add_u64 v[18:19], v[18:19], 0, s[14:15]
	global_load_dword v203, v[18:19], off
	v_lshl_add_u64 v[18:19], v[18:19], 0, s[14:15]
	global_load_dword v204, v[18:19], off
	v_lshl_add_u64 v[18:19], v[18:19], 0, s[14:15]
	global_load_dword v205, v[18:19], off
	v_lshl_add_u64 v[18:19], v[18:19], 0, s[14:15]
	global_load_dword v206, v[18:19], off
	v_lshl_add_u64 v[18:19], v[18:19], 0, s[14:15]
	global_load_dword v207, v[18:19], off
	v_lshl_add_u64 v[18:19], v[18:19], 0, s[14:15]
	global_load_dword v208, v[18:19], off
	v_lshl_add_u64 v[18:19], v[18:19], 0, s[14:15]
	global_load_dword v209, v[18:19], off
	v_lshl_add_u64 v[18:19], v[18:19], 0, s[14:15]
	global_load_dword v210, v[18:19], off
	v_lshl_add_u64 v[18:19], v[18:19], 0, s[14:15]
	global_load_dword v211, v[18:19], off
	v_lshl_add_u64 v[18:19], v[18:19], 0, s[14:15]
	global_load_dword v212, v[18:19], off
	v_lshl_add_u64 v[18:19], v[18:19], 0, s[14:15]
	global_load_dword v213, v[18:19], off
	v_lshl_add_u64 v[18:19], v[18:19], 0, s[14:15]
	global_load_dword v214, v[18:19], off
	v_lshl_add_u64 v[18:19], v[18:19], 0, s[14:15]
	global_load_dword v215, v[18:19], off
	v_lshl_add_u64 v[18:19], v[18:19], 0, s[14:15]
	global_load_dword v216, v[18:19], off
	v_lshl_add_u64 v[18:19], v[18:19], 0, s[14:15]
	global_load_dword v217, v[18:19], off
	v_mbcnt_lo_u32_b32 v20, -1, 0
	v_mbcnt_hi_u32_b32 v20, -1, v20
	v_and_b32_e32 v20, 15, v20
	v_lshl_add_u32 v21, v20, 12, v45
	ds_read_b128 v[182:185], v21
	ds_read_b128 v[218:221], v21 offset:16
	s_waitcnt vmcnt(28) lgkmcnt(1)
	v_mfma_f32_16x16x4_f32 v[14:17], v182, v186, v[14:17]
	v_mfma_f32_16x16x4_f32 v[14:17], v183, v187, v[14:17]
	v_mfma_f32_16x16x4_f32 v[14:17], v184, v188, v[14:17]
	v_mfma_f32_16x16x4_f32 v[14:17], v185, v189, v[14:17]
	ds_read_b128 v[182:185], v21 offset:32
	s_waitcnt vmcnt(24) lgkmcnt(1)
	v_mfma_f32_16x16x4_f32 v[14:17], v218, v190, v[14:17]
	v_mfma_f32_16x16x4_f32 v[14:17], v219, v191, v[14:17]
	v_mfma_f32_16x16x4_f32 v[14:17], v220, v192, v[14:17]
	v_mfma_f32_16x16x4_f32 v[14:17], v221, v193, v[14:17]
	ds_read_b128 v[218:221], v21 offset:48
	s_waitcnt vmcnt(20) lgkmcnt(1)
	v_mfma_f32_16x16x4_f32 v[14:17], v182, v194, v[14:17]
	v_mfma_f32_16x16x4_f32 v[14:17], v183, v195, v[14:17]
	v_mfma_f32_16x16x4_f32 v[14:17], v184, v196, v[14:17]
	v_mfma_f32_16x16x4_f32 v[14:17], v185, v197, v[14:17]
	ds_read_b128 v[182:185], v21 offset:64
	s_waitcnt vmcnt(16) lgkmcnt(1)
	v_mfma_f32_16x16x4_f32 v[14:17], v218, v198, v[14:17]
	v_mfma_f32_16x16x4_f32 v[14:17], v219, v199, v[14:17]
	v_mfma_f32_16x16x4_f32 v[14:17], v220, v200, v[14:17]
	v_mfma_f32_16x16x4_f32 v[14:17], v221, v201, v[14:17]
	ds_read_b128 v[218:221], v21 offset:80
	s_waitcnt vmcnt(12) lgkmcnt(1)
	v_mfma_f32_16x16x4_f32 v[14:17], v182, v202, v[14:17]
	v_mfma_f32_16x16x4_f32 v[14:17], v183, v203, v[14:17]
	v_mfma_f32_16x16x4_f32 v[14:17], v184, v204, v[14:17]
	v_mfma_f32_16x16x4_f32 v[14:17], v185, v205, v[14:17]
	ds_read_b128 v[182:185], v21 offset:96
	s_waitcnt vmcnt(8) lgkmcnt(1)
	v_mfma_f32_16x16x4_f32 v[14:17], v218, v206, v[14:17]
	v_mfma_f32_16x16x4_f32 v[14:17], v219, v207, v[14:17]
	v_mfma_f32_16x16x4_f32 v[14:17], v220, v208, v[14:17]
	v_mfma_f32_16x16x4_f32 v[14:17], v221, v209, v[14:17]
	ds_read_b128 v[218:221], v21 offset:112
	s_waitcnt vmcnt(4) lgkmcnt(1)
	v_mfma_f32_16x16x4_f32 v[14:17], v182, v210, v[14:17]
	v_mfma_f32_16x16x4_f32 v[14:17], v183, v211, v[14:17]
	v_mfma_f32_16x16x4_f32 v[14:17], v184, v212, v[14:17]
	v_mfma_f32_16x16x4_f32 v[14:17], v185, v213, v[14:17]
	s_waitcnt vmcnt(0) lgkmcnt(0)
	v_mfma_f32_16x16x4_f32 v[14:17], v218, v214, v[14:17]
	v_mfma_f32_16x16x4_f32 v[14:17], v219, v215, v[14:17]
	v_mfma_f32_16x16x4_f32 v[14:17], v220, v216, v[14:17]
	v_mfma_f32_16x16x4_f32 v[14:17], v221, v217, v[14:17]
	s_nop 7
	s_nop 3
	v_mbcnt_lo_u32_b32 v20, -1, 0
	v_mbcnt_hi_u32_b32 v20, -1, v20
	v_lshrrev_b32_e32 v20, 4, v20
	v_lshl_add_u32 v20, v20, 8, v46
	ds_write_b32 v20, v14
	ds_write_b32 v20, v15 offset:64
	ds_write_b32 v20, v16 offset:128
	ds_write_b32 v20, v17 offset:192
	v_lshl_or_b32 v0, s2, 4, v35
	s_movk_i32 s3, 0x1000
	v_cmp_gt_i32_e32 vcc, s3, v0
	s_and_b64 s[18:19], s[6:7], vcc
	s_waitcnt lgkmcnt(0)
	s_barrier
	s_and_saveexec_b64 s[14:15], s[18:19]
	s_cbranch_execz .LBB0_1051
	ds_read2st64_b32 v[2:3], v41 offset1:4
	s_waitcnt lgkmcnt(0)
	v_add_f32_e32 v1, 0, v2
	v_add_f32_e32 v1, v1, v3
	ds_read2st64_b32 v[2:3], v41 offset0:8 offset1:12
	s_waitcnt lgkmcnt(0)
	v_add_f32_e32 v1, v1, v2
	v_add_f32_e32 v1, v1, v3
	ds_read2st64_b32 v[2:3], v41 offset0:16 offset1:20
	s_waitcnt lgkmcnt(0)
	v_add_f32_e32 v1, v1, v2
	v_add_f32_e32 v1, v1, v3
	ds_read2st64_b32 v[2:3], v41 offset0:24 offset1:28
	s_waitcnt lgkmcnt(0)
	v_add_f32_e32 v1, v1, v2
	ds_read_b32 v2, v42
	v_add_f32_e32 v1, v1, v3
	s_waitcnt lgkmcnt(0)
	v_mul_f32_e32 v2, v1, v2
	v_ashrrev_i32_e32 v1, 31, v0
	v_max_f32_e32 v2, 0, v2
	v_lshl_add_u64 v[0:1], v[0:1], 2, v[4:5]
	v_mul_f32_e32 v2, v2, v2
	global_store_dword v[0:1], v2, off
	s_branch .LBB0_1051

; template <int M> DEVI float shx(float v) { return __int_as_float(__builtin_amdgcn_ds_swizzle(__float_as_int(v), (M << 10) | 0x1f)); }
; DEVI float shx32(float v, int lane) { return __int_as_float(__builtin_amdgcn_ds_bpermute((lane ^ 32) << 2, __float_as_int(v))); }
; DEVI void sk_gemm(const float* __restrict__ A, int lda, int K, const float* __restrict__ W, int N, const float* __restrict__ gain,
;                   bool use_rs, float* __restrict__ out, int ldo, int mode, unsigned char* lds, int wv, int bid, int nblk) {
;     ...
; #pragma unroll 2
;       for (int k = 0; k < ks; k += 4) {
;         const float w0 = Wp[(size_t)(k + 0) * N], w1 = Wp[(size_t)(k + 1) * N], w2 = Wp[(size_t)(k + 2) * N], w3 = Wp[(size_t)(k + 3) * N];
; #pragma unroll
;         for (int b = 0; b < 16; ++b) { const float4 a = *(const float4*)(Ap + b * 1024 + k); acc[b] += a.x * w0 + a.y * w1 + a.z * w2 + a.w * w3; }
;       }
;     }
; #pragma unroll
;     for (int b = 0; b < 16; ++b) { float v = acc[b]; v += shx<16>(v); v += shx32(v, lane); if (kq == 0) red[(wave * 16 + b) * 16 + c16] = v; }
;     __syncthreads();
;     if (tid < 256) {
;       const int b = tid >> 4, c = tid & 15; float v = 0.f;
; #pragma unroll
;       for (int w = 0; w < 8; ++w) v += red[(w * 16 + b) * 16 + c];
;       const int nn = grp * 16 + c;
;       if (nn < N) {
;         if (use_rs) v *= rsS[b];
;         float* o = out + (size_t)b * ldo + nn;
;         if (mode == 1) *o += v; else if (mode == 2) { v = fmaxf(v, 0.f); *o = v * v; } else *o = v;
.LBB0_1098:
	s_mov_b32 s6, 0xffff9000
	s_mov_b32 s7, -1
	v_lshl_add_u64 v[152:153], v[146:147], 0, s[6:7]
	s_mov_b64 s[6:7], 0x1000
	global_load_dword v186, v[152:153], off
	v_lshl_add_u64 v[152:153], v[152:153], 0, s[6:7]
	global_load_dword v187, v[152:153], off
	v_lshl_add_u64 v[152:153], v[152:153], 0, s[6:7]
	global_load_dword v188, v[152:153], off
	v_lshl_add_u64 v[152:153], v[152:153], 0, s[6:7]
	global_load_dword v189, v[152:153], off
	v_lshl_add_u64 v[152:153], v[152:153], 0, s[6:7]
	global_load_dword v190, v[152:153], off
	v_lshl_add_u64 v[152:153], v[152:153], 0, s[6:7]
	global_load_dword v191, v[152:153], off
	v_lshl_add_u64 v[152:153], v[152:153], 0, s[6:7]
	global_load_dword v192, v[152:153], off
	v_lshl_add_u64 v[152:153], v[152:153], 0, s[6:7]
	global_load_dword v193, v[152:153], off
	v_lshl_add_u64 v[152:153], v[152:153], 0, s[6:7]
	global_load_dword v194, v[152:153], off
	v_lshl_add_u64 v[152:153], v[152:153], 0, s[6:7]
	global_load_dword v195, v[152:153], off
	v_lshl_add_u64 v[152:153], v[152:153], 0, s[6:7]
	global_load_dword v196, v[152:153], off
	v_lshl_add_u64 v[152:153], v[152:153], 0, s[6:7]
	global_load_dword v197, v[152:153], off
	v_lshl_add_u64 v[152:153], v[152:153], 0, s[6:7]
	global_load_dword v198, v[152:153], off
	v_lshl_add_u64 v[152:153], v[152:153], 0, s[6:7]
	global_load_dword v199, v[152:153], off
	v_lshl_add_u64 v[152:153], v[152:153], 0, s[6:7]
	global_load_dword v200, v[152:153], off
	v_lshl_add_u64 v[152:153], v[152:153], 0, s[6:7]
	global_load_dword v201, v[152:153], off
	v_lshl_add_u64 v[152:153], v[152:153], 0, s[6:7]
	global_load_dword v202, v[152:153], off
	v_lshl_add_u64 v[152:153], v[152:153], 0, s[6:7]
	global_load_dword v203, v[152:153], off
	v_lshl_add_u64 v[152:153], v[152:153], 0, s[6:7]
	global_load_dword v204, v[152:153], off
	v_lshl_add_u64 v[152:153], v[152:153], 0, s[6:7]
	global_load_dword v205, v[152:153], off
	v_lshl_add_u64 v[152:153], v[152:153], 0, s[6:7]
	global_load_dword v206, v[152:153], off
	v_lshl_add_u64 v[152:153], v[152:153], 0, s[6:7]
	global_load_dword v207, v[152:153], off
	v_lshl_add_u64 v[152:153], v[152:153], 0, s[6:7]
	global_load_dword v208, v[152:153], off
	v_lshl_add_u64 v[152:153], v[152:153], 0, s[6:7]
	global_load_dword v209, v[152:153], off
	v_lshl_add_u64 v[152:153], v[152:153], 0, s[6:7]
	global_load_dword v210, v[152:153], off
	v_lshl_add_u64 v[152:153], v[152:153], 0, s[6:7]
	global_load_dword v211, v[152:153], off
	v_lshl_add_u64 v[152:153], v[152:153], 0, s[6:7]
	global_load_dword v212, v[152:153], off
	v_lshl_add_u64 v[152:153], v[152:153], 0, s[6:7]
	global_load_dword v213, v[152:153], off
	v_lshl_add_u64 v[152:153], v[152:153], 0, s[6:7]
	global_load_dword v214, v[152:153], off
	v_lshl_add_u64 v[152:153], v[152:153], 0, s[6:7]
	global_load_dword v215, v[152:153], off
	v_lshl_add_u64 v[152:153], v[152:153], 0, s[6:7]
	global_load_dword v216, v[152:153], off
	v_lshl_add_u64 v[152:153], v[152:153], 0, s[6:7]
	global_load_dword v217, v[152:153], off
	v_mbcnt_lo_u32_b32 v154, -1, 0
	v_mbcnt_hi_u32_b32 v154, -1, v154
	v_and_b32_e32 v154, 15, v154
	v_lshl_add_u32 v155, v154, 12, v172
	ds_read_b128 v[182:185], v155
	ds_read_b128 v[218:221], v155 offset:16
	s_waitcnt vmcnt(28) lgkmcnt(1)
	v_mfma_f32_16x16x4_f32 v[148:151], v182, v186, v[148:151]
	v_mfma_f32_16x16x4_f32 v[148:151], v183, v187, v[148:151]
	v_mfma_f32_16x16x4_f32 v[148:151], v184, v188, v[148:151]
	v_mfma_f32_16x16x4_f32 v[148:151], v185, v189, v[148:151]
	ds_read_b128 v[182:185], v155 offset:32
	s_waitcnt vmcnt(24) lgkmcnt(1)
	v_mfma_f32_16x16x4_f32 v[148:151], v218, v190, v[148:151]
	v_mfma_f32_16x16x4_f32 v[148:151], v219, v191, v[148:151]
	v_mfma_f32_16x16x4_f32 v[148:151], v220, v192, v[148:151]
	v_mfma_f32_16x16x4_f32 v[148:151], v221, v193, v[148:151]
	ds_read_b128 v[218:221], v155 offset:48
	s_waitcnt vmcnt(20) lgkmcnt(1)
	v_mfma_f32_16x16x4_f32 v[148:151], v182, v194, v[148:151]
	v_mfma_f32_16x16x4_f32 v[148:151], v183, v195, v[148:151]
	v_mfma_f32_16x16x4_f32 v[148:151], v184, v196, v[148:151]
	v_mfma_f32_16x16x4_f32 v[148:151], v185, v197, v[148:151]
	ds_read_b128 v[182:185], v155 offset:64
	s_waitcnt vmcnt(16) lgkmcnt(1)
	v_mfma_f32_16x16x4_f32 v[148:151], v218, v198, v[148:151]
	v_mfma_f32_16x16x4_f32 v[148:151], v219, v199, v[148:151]
	v_mfma_f32_16x16x4_f32 v[148:151], v220, v200, v[148:151]
	v_mfma_f32_16x16x4_f32 v[148:151], v221, v201, v[148:151]
	ds_read_b128 v[218:221], v155 offset:80
	s_waitcnt vmcnt(12) lgkmcnt(1)
	v_mfma_f32_16x16x4_f32 v[148:151], v182, v202, v[148:151]
	v_mfma_f32_16x16x4_f32 v[148:151], v183, v203, v[148:151]
	v_mfma_f32_16x16x4_f32 v[148:151], v184, v204, v[148:151]
	v_mfma_f32_16x16x4_f32 v[148:151], v185, v205, v[148:151]
	ds_read_b128 v[182:185], v155 offset:96
	s_waitcnt vmcnt(8) lgkmcnt(1)
	v_mfma_f32_16x16x4_f32 v[148:151], v218, v206, v[148:151]
	v_mfma_f32_16x16x4_f32 v[148:151], v219, v207, v[148:151]
	v_mfma_f32_16x16x4_f32 v[148:151], v220, v208, v[148:151]
	v_mfma_f32_16x16x4_f32 v[148:151], v221, v209, v[148:151]
	ds_read_b128 v[218:221], v155 offset:112
	s_waitcnt vmcnt(4) lgkmcnt(1)
	v_mfma_f32_16x16x4_f32 v[148:151], v182, v210, v[148:151]
	v_mfma_f32_16x16x4_f32 v[148:151], v183, v211, v[148:151]
	v_mfma_f32_16x16x4_f32 v[148:151], v184, v212, v[148:151]
	v_mfma_f32_16x16x4_f32 v[148:151], v185, v213, v[148:151]
	s_waitcnt vmcnt(0) lgkmcnt(0)
	v_mfma_f32_16x16x4_f32 v[148:151], v218, v214, v[148:151]
	v_mfma_f32_16x16x4_f32 v[148:151], v219, v215, v[148:151]
	v_mfma_f32_16x16x4_f32 v[148:151], v220, v216, v[148:151]
	v_mfma_f32_16x16x4_f32 v[148:151], v221, v217, v[148:151]
	s_nop 7
	s_nop 3
	v_mbcnt_lo_u32_b32 v154, -1, 0
	v_mbcnt_hi_u32_b32 v154, -1, v154
	v_lshrrev_b32_e32 v154, 4, v154
	v_lshl_add_u32 v154, v154, 8, v173
	ds_write_b32 v154, v148
	ds_write_b32 v154, v149 offset:64
	ds_write_b32 v154, v150 offset:128
	ds_write_b32 v154, v151 offset:192
	v_lshl_or_b32 v0, s2, 4, v131
	s_movk_i32 s3, 0x400
	v_cmp_gt_i32_e64 s[4:5], s3, v0
	s_and_b64 s[6:7], s[0:1], s[4:5]
	s_waitcnt lgkmcnt(0)
	s_barrier
	s_and_saveexec_b64 s[4:5], s[6:7]
	s_cbranch_execz .LBB0_1096
	ds_read2st64_b32 v[2:3], v170 offset1:4
	v_ashrrev_i32_e32 v1, 31, v0
	v_lshl_add_u64 v[0:1], v[0:1], 2, v[4:5]
	s_waitcnt lgkmcnt(0)
	v_add_f32_e32 v2, 0, v2
	v_add_f32_e32 v32, v2, v3
	ds_read2st64_b32 v[2:3], v170 offset0:8 offset1:12
	s_waitcnt lgkmcnt(0)
	v_add_f32_e32 v2, v32, v2
	v_add_f32_e32 v32, v2, v3
	ds_read2st64_b32 v[2:3], v170 offset0:16 offset1:20
	s_waitcnt lgkmcnt(0)
	v_add_f32_e32 v2, v32, v2
	v_add_f32_e32 v32, v2, v3
	ds_read2st64_b32 v[2:3], v170 offset0:24 offset1:28
	s_waitcnt lgkmcnt(0)
	v_add_f32_e32 v2, v32, v2
	v_add_f32_e32 v2, v2, v3
	global_load_dword v3, v[0:1], off
	s_waitcnt vmcnt(0)
	v_add_f32_e32 v2, v2, v3
	global_store_dword v[0:1], v2, off
	s_branch .LBB0_1096

; template <int M> DEVI float shx(float v) { return __int_as_float(__builtin_amdgcn_ds_swizzle(__float_as_int(v), (M << 10) | 0x1f)); }
; DEVI float shx32(float v, int lane) { return __int_as_float(__builtin_amdgcn_ds_bpermute((lane ^ 32) << 2, __float_as_int(v))); }
; DEVI void sk_gemm(const float* __restrict__ A, int lda, int K, const float* __restrict__ W, int N, const float* __restrict__ gain,
;                   bool use_rs, float* __restrict__ out, int ldo, int mode, unsigned char* lds, int wv, int bid, int nblk) {
;     ...
; #pragma unroll 2
;       for (int k = 0; k < ks; k += 4) {
;         const float w0 = Wp[(size_t)(k + 0) * N], w1 = Wp[(size_t)(k + 1) * N], w2 = Wp[(size_t)(k + 2) * N], w3 = Wp[(size_t)(k + 3) * N];
; #pragma unroll
;         for (int b = 0; b < 16; ++b) { const float4 a = *(const float4*)(Ap + b * 1024 + k); acc[b] += a.x * w0 + a.y * w1 + a.z * w2 + a.w * w3; }
;       }
;     }
; #pragma unroll
;     for (int b = 0; b < 16; ++b) { float v = acc[b]; v += shx<16>(v); v += shx32(v, lane); if (kq == 0) red[(wave * 16 + b) * 16 + c16] = v; }
;     __syncthreads();
;     if (tid < 256) {
;       const int b = tid >> 4, c = tid & 15; float v = 0.f;
; #pragma unroll
;       for (int w = 0; w < 8; ++w) v += red[(w * 16 + b) * 16 + c];
;       const int nn = grp * 16 + c;
;       if (nn < N) {
;         if (use_rs) v *= rsS[b];
;         float* o = out + (size_t)b * ldo + nn;
;         if (mode == 1) *o += v; else if (mode == 2) { v = fmaxf(v, 0.f); *o = v * v; } else *o = v;
.LBB0_1166:
	s_mov_b32 s18, 0xfffec688
	s_mov_b32 s19, -1
	v_lshl_add_u64 v[18:19], v[12:13], 0, s[18:19]
	s_mov_b64 s[18:19], 0x2cc8
	global_load_dword v186, v[18:19], off
	v_lshl_add_u64 v[18:19], v[18:19], 0, s[18:19]
	global_load_dword v187, v[18:19], off
	v_lshl_add_u64 v[18:19], v[18:19], 0, s[18:19]
	global_load_dword v188, v[18:19], off
	v_lshl_add_u64 v[18:19], v[18:19], 0, s[18:19]
	global_load_dword v189, v[18:19], off
	v_lshl_add_u64 v[18:19], v[18:19], 0, s[18:19]
	global_load_dword v190, v[18:19], off
	v_lshl_add_u64 v[18:19], v[18:19], 0, s[18:19]
	global_load_dword v191, v[18:19], off
	v_lshl_add_u64 v[18:19], v[18:19], 0, s[18:19]
	global_load_dword v192, v[18:19], off
	v_lshl_add_u64 v[18:19], v[18:19], 0, s[18:19]
	global_load_dword v193, v[18:19], off
	v_lshl_add_u64 v[18:19], v[18:19], 0, s[18:19]
	global_load_dword v194, v[18:19], off
	v_lshl_add_u64 v[18:19], v[18:19], 0, s[18:19]
	global_load_dword v195, v[18:19], off
	v_lshl_add_u64 v[18:19], v[18:19], 0, s[18:19]
	global_load_dword v196, v[18:19], off
	v_lshl_add_u64 v[18:19], v[18:19], 0, s[18:19]
	global_load_dword v197, v[18:19], off
	v_lshl_add_u64 v[18:19], v[18:19], 0, s[18:19]
	global_load_dword v198, v[18:19], off
	v_lshl_add_u64 v[18:19], v[18:19], 0, s[18:19]
	global_load_dword v199, v[18:19], off
	v_lshl_add_u64 v[18:19], v[18:19], 0, s[18:19]
	global_load_dword v200, v[18:19], off
	v_lshl_add_u64 v[18:19], v[18:19], 0, s[18:19]
	global_load_dword v201, v[18:19], off
	v_lshl_add_u64 v[18:19], v[18:19], 0, s[18:19]
	global_load_dword v202, v[18:19], off
	v_lshl_add_u64 v[18:19], v[18:19], 0, s[18:19]
	global_load_dword v203, v[18:19], off
	v_lshl_add_u64 v[18:19], v[18:19], 0, s[18:19]
	global_load_dword v204, v[18:19], off
	v_lshl_add_u64 v[18:19], v[18:19], 0, s[18:19]
	global_load_dword v205, v[18:19], off
	v_lshl_add_u64 v[18:19], v[18:19], 0, s[18:19]
	global_load_dword v206, v[18:19], off
	v_lshl_add_u64 v[18:19], v[18:19], 0, s[18:19]
	global_load_dword v207, v[18:19], off
	v_lshl_add_u64 v[18:19], v[18:19], 0, s[18:19]
	global_load_dword v208, v[18:19], off
	v_lshl_add_u64 v[18:19], v[18:19], 0, s[18:19]
	global_load_dword v209, v[18:19], off
	v_lshl_add_u64 v[18:19], v[18:19], 0, s[18:19]
	global_load_dword v210, v[18:19], off
	v_lshl_add_u64 v[18:19], v[18:19], 0, s[18:19]
	global_load_dword v211, v[18:19], off
	v_lshl_add_u64 v[18:19], v[18:19], 0, s[18:19]
	global_load_dword v212, v[18:19], off
	v_lshl_add_u64 v[18:19], v[18:19], 0, s[18:19]
	global_load_dword v213, v[18:19], off
	v_lshl_add_u64 v[18:19], v[18:19], 0, s[18:19]
	global_load_dword v214, v[18:19], off
	v_lshl_add_u64 v[18:19], v[18:19], 0, s[18:19]
	global_load_dword v215, v[18:19], off
	v_lshl_add_u64 v[18:19], v[18:19], 0, s[18:19]
	global_load_dword v216, v[18:19], off
	v_lshl_add_u64 v[18:19], v[18:19], 0, s[18:19]
	global_load_dword v217, v[18:19], off
	v_mbcnt_lo_u32_b32 v20, -1, 0
	v_mbcnt_hi_u32_b32 v20, -1, v20
	v_and_b32_e32 v20, 15, v20
	v_lshl_add_u32 v21, v20, 12, v45
	ds_read_b128 v[182:185], v21
	ds_read_b128 v[218:221], v21 offset:16
	s_waitcnt vmcnt(28) lgkmcnt(1)
	v_mfma_f32_16x16x4_f32 v[14:17], v182, v186, v[14:17]
	v_mfma_f32_16x16x4_f32 v[14:17], v183, v187, v[14:17]
	v_mfma_f32_16x16x4_f32 v[14:17], v184, v188, v[14:17]
	v_mfma_f32_16x16x4_f32 v[14:17], v185, v189, v[14:17]
	ds_read_b128 v[182:185], v21 offset:32
	s_waitcnt vmcnt(24) lgkmcnt(1)
	v_mfma_f32_16x16x4_f32 v[14:17], v218, v190, v[14:17]
	v_mfma_f32_16x16x4_f32 v[14:17], v219, v191, v[14:17]
	v_mfma_f32_16x16x4_f32 v[14:17], v220, v192, v[14:17]
	v_mfma_f32_16x16x4_f32 v[14:17], v221, v193, v[14:17]
	ds_read_b128 v[218:221], v21 offset:48
	s_waitcnt vmcnt(20) lgkmcnt(1)
	v_mfma_f32_16x16x4_f32 v[14:17], v182, v194, v[14:17]
	v_mfma_f32_16x16x4_f32 v[14:17], v183, v195, v[14:17]
	v_mfma_f32_16x16x4_f32 v[14:17], v184, v196, v[14:17]
	v_mfma_f32_16x16x4_f32 v[14:17], v185, v197, v[14:17]
	ds_read_b128 v[182:185], v21 offset:64
	s_waitcnt vmcnt(16) lgkmcnt(1)
	v_mfma_f32_16x16x4_f32 v[14:17], v218, v198, v[14:17]
	v_mfma_f32_16x16x4_f32 v[14:17], v219, v199, v[14:17]
	v_mfma_f32_16x16x4_f32 v[14:17], v220, v200, v[14:17]
	v_mfma_f32_16x16x4_f32 v[14:17], v221, v201, v[14:17]
	ds_read_b128 v[218:221], v21 offset:80
	s_waitcnt vmcnt(12) lgkmcnt(1)
	v_mfma_f32_16x16x4_f32 v[14:17], v182, v202, v[14:17]
	v_mfma_f32_16x16x4_f32 v[14:17], v183, v203, v[14:17]
	v_mfma_f32_16x16x4_f32 v[14:17], v184, v204, v[14:17]
	v_mfma_f32_16x16x4_f32 v[14:17], v185, v205, v[14:17]
	ds_read_b128 v[182:185], v21 offset:96
	s_waitcnt vmcnt(8) lgkmcnt(1)
	v_mfma_f32_16x16x4_f32 v[14:17], v218, v206, v[14:17]
	v_mfma_f32_16x16x4_f32 v[14:17], v219, v207, v[14:17]
	v_mfma_f32_16x16x4_f32 v[14:17], v220, v208, v[14:17]
	v_mfma_f32_16x16x4_f32 v[14:17], v221, v209, v[14:17]
	ds_read_b128 v[218:221], v21 offset:112
	s_waitcnt vmcnt(4) lgkmcnt(1)
	v_mfma_f32_16x16x4_f32 v[14:17], v182, v210, v[14:17]
	v_mfma_f32_16x16x4_f32 v[14:17], v183, v211, v[14:17]
	v_mfma_f32_16x16x4_f32 v[14:17], v184, v212, v[14:17]
	v_mfma_f32_16x16x4_f32 v[14:17], v185, v213, v[14:17]
	s_waitcnt vmcnt(0) lgkmcnt(0)
	v_mfma_f32_16x16x4_f32 v[14:17], v218, v214, v[14:17]
	v_mfma_f32_16x16x4_f32 v[14:17], v219, v215, v[14:17]
	v_mfma_f32_16x16x4_f32 v[14:17], v220, v216, v[14:17]
	v_mfma_f32_16x16x4_f32 v[14:17], v221, v217, v[14:17]
	s_nop 7
	s_nop 3
	v_mbcnt_lo_u32_b32 v20, -1, 0
	v_mbcnt_hi_u32_b32 v20, -1, v20
	v_lshrrev_b32_e32 v20, 4, v20
	v_lshl_add_u32 v20, v20, 8, v46
	ds_write_b32 v20, v14
	ds_write_b32 v20, v15 offset:64
	ds_write_b32 v20, v16 offset:128
	ds_write_b32 v20, v17 offset:192
	v_lshl_or_b32 v0, s2, 4, v35
	s_movk_i32 s3, 0xb32
	v_cmp_gt_i32_e32 vcc, s3, v0
	s_and_b64 s[14:15], s[6:7], vcc
	s_waitcnt lgkmcnt(0)
	s_barrier
	s_and_saveexec_b64 s[12:13], s[14:15]
	s_cbranch_execz .LBB0_1160
	ds_read2st64_b32 v[2:3], v41 offset1:4
	v_ashrrev_i32_e32 v1, 31, v0
	v_lshl_add_u64 v[0:1], v[0:1], 2, v[4:5]
	s_waitcnt lgkmcnt(0)
	v_add_f32_e32 v2, 0, v2
	v_add_f32_e32 v11, v2, v3
	ds_read2st64_b32 v[2:3], v41 offset0:8 offset1:12
	s_waitcnt lgkmcnt(0)
	v_add_f32_e32 v2, v11, v2
	v_add_f32_e32 v11, v2, v3
	ds_read2st64_b32 v[2:3], v41 offset0:16 offset1:20
	s_waitcnt lgkmcnt(0)
	v_add_f32_e32 v2, v11, v2
	v_add_f32_e32 v11, v2, v3
	ds_read2st64_b32 v[2:3], v41 offset0:24 offset1:28
	s_waitcnt lgkmcnt(0)
	v_add_f32_e32 v2, v11, v2
	v_add_f32_e32 v2, v2, v3
	ds_read_b32 v3, v42
	s_waitcnt lgkmcnt(0)
	v_mul_f32_e32 v2, v2, v3
	global_store_dword v[0:1], v2, off
	s_branch .LBB0_1160

; template <int M> DEVI float shx(float v) { return __int_as_float(__builtin_amdgcn_ds_swizzle(__float_as_int(v), (M << 10) | 0x1f)); }
; DEVI float shx32(float v, int lane) { return __int_as_float(__builtin_amdgcn_ds_bpermute((lane ^ 32) << 2, __float_as_int(v))); }
; DEVI void sk_gemm(const float* __restrict__ A, int lda, int K, const float* __restrict__ W, int N, const float* __restrict__ gain,
;                   bool use_rs, float* __restrict__ out, int ldo, int mode, unsigned char* lds, int wv, int bid, int nblk) {
;     ...
; #pragma unroll 2
;       for (int k = 0; k < ks; k += 4) {
;         const float w0 = Wp[(size_t)(k + 0) * N], w1 = Wp[(size_t)(k + 1) * N], w2 = Wp[(size_t)(k + 2) * N], w3 = Wp[(size_t)(k + 3) * N];
; #pragma unroll
;         for (int b = 0; b < 16; ++b) { const float4 a = *(const float4*)(Ap + b * 1024 + k); acc[b] += a.x * w0 + a.y * w1 + a.z * w2 + a.w * w3; }
;       }
;     }
; #pragma unroll
;     for (int b = 0; b < 16; ++b) { float v = acc[b]; v += shx<16>(v); v += shx32(v, lane); if (kq == 0) red[(wave * 16 + b) * 16 + c16] = v; }
;     __syncthreads();
;     if (tid < 256) {
;       const int b = tid >> 4, c = tid & 15; float v = 0.f;
; #pragma unroll
;       for (int w = 0; w < 8; ++w) v += red[(w * 16 + b) * 16 + c];
;       const int nn = grp * 16 + c;
;       if (nn < N) {
;         if (use_rs) v *= rsS[b];
;         float* o = out + (size_t)b * ldo + nn;
;         if (mode == 1) *o += v; else if (mode == 2) { v = fmaxf(v, 0.f); *o = v * v; } else *o = v;
.LBB0_1674:
	s_mov_b32 s16, 0xfffec688
	s_mov_b32 s17, -1
	v_lshl_add_u64 v[18:19], v[12:13], 0, s[16:17]
	s_mov_b64 s[16:17], 0x2cc8
	global_load_dword v186, v[18:19], off
	v_lshl_add_u64 v[18:19], v[18:19], 0, s[16:17]
	global_load_dword v187, v[18:19], off
	v_lshl_add_u64 v[18:19], v[18:19], 0, s[16:17]
	global_load_dword v188, v[18:19], off
	v_lshl_add_u64 v[18:19], v[18:19], 0, s[16:17]
	global_load_dword v189, v[18:19], off
	v_lshl_add_u64 v[18:19], v[18:19], 0, s[16:17]
	global_load_dword v190, v[18:19], off
	v_lshl_add_u64 v[18:19], v[18:19], 0, s[16:17]
	global_load_dword v191, v[18:19], off
	v_lshl_add_u64 v[18:19], v[18:19], 0, s[16:17]
	global_load_dword v192, v[18:19], off
	v_lshl_add_u64 v[18:19], v[18:19], 0, s[16:17]
	global_load_dword v193, v[18:19], off
	v_lshl_add_u64 v[18:19], v[18:19], 0, s[16:17]
	global_load_dword v194, v[18:19], off
	v_lshl_add_u64 v[18:19], v[18:19], 0, s[16:17]
	global_load_dword v195, v[18:19], off
	v_lshl_add_u64 v[18:19], v[18:19], 0, s[16:17]
	global_load_dword v196, v[18:19], off
	v_lshl_add_u64 v[18:19], v[18:19], 0, s[16:17]
	global_load_dword v197, v[18:19], off
	v_lshl_add_u64 v[18:19], v[18:19], 0, s[16:17]
	global_load_dword v198, v[18:19], off
	v_lshl_add_u64 v[18:19], v[18:19], 0, s[16:17]
	global_load_dword v199, v[18:19], off
	v_lshl_add_u64 v[18:19], v[18:19], 0, s[16:17]
	global_load_dword v200, v[18:19], off
	v_lshl_add_u64 v[18:19], v[18:19], 0, s[16:17]
	global_load_dword v201, v[18:19], off
	v_lshl_add_u64 v[18:19], v[18:19], 0, s[16:17]
	global_load_dword v202, v[18:19], off
	v_lshl_add_u64 v[18:19], v[18:19], 0, s[16:17]
	global_load_dword v203, v[18:19], off
	v_lshl_add_u64 v[18:19], v[18:19], 0, s[16:17]
	global_load_dword v204, v[18:19], off
	v_lshl_add_u64 v[18:19], v[18:19], 0, s[16:17]
	global_load_dword v205, v[18:19], off
	v_lshl_add_u64 v[18:19], v[18:19], 0, s[16:17]
	global_load_dword v206, v[18:19], off
	v_lshl_add_u64 v[18:19], v[18:19], 0, s[16:17]
	global_load_dword v207, v[18:19], off
	v_lshl_add_u64 v[18:19], v[18:19], 0, s[16:17]
	global_load_dword v208, v[18:19], off
	v_lshl_add_u64 v[18:19], v[18:19], 0, s[16:17]
	global_load_dword v209, v[18:19], off
	v_lshl_add_u64 v[18:19], v[18:19], 0, s[16:17]
	global_load_dword v210, v[18:19], off
	v_lshl_add_u64 v[18:19], v[18:19], 0, s[16:17]
	global_load_dword v211, v[18:19], off
	v_lshl_add_u64 v[18:19], v[18:19], 0, s[16:17]
	global_load_dword v212, v[18:19], off
	v_lshl_add_u64 v[18:19], v[18:19], 0, s[16:17]
	global_load_dword v213, v[18:19], off
	v_lshl_add_u64 v[18:19], v[18:19], 0, s[16:17]
	global_load_dword v214, v[18:19], off
	v_lshl_add_u64 v[18:19], v[18:19], 0, s[16:17]
	global_load_dword v215, v[18:19], off
	v_lshl_add_u64 v[18:19], v[18:19], 0, s[16:17]
	global_load_dword v216, v[18:19], off
	v_lshl_add_u64 v[18:19], v[18:19], 0, s[16:17]
	global_load_dword v217, v[18:19], off
	v_mbcnt_lo_u32_b32 v20, -1, 0
	v_mbcnt_hi_u32_b32 v20, -1, v20
	v_and_b32_e32 v20, 15, v20
	v_lshl_add_u32 v21, v20, 12, v45
	ds_read_b128 v[182:185], v21
	ds_read_b128 v[218:221], v21 offset:16
	s_waitcnt vmcnt(28) lgkmcnt(1)
	v_mfma_f32_16x16x4_f32 v[14:17], v182, v186, v[14:17]
	v_mfma_f32_16x16x4_f32 v[14:17], v183, v187, v[14:17]
	v_mfma_f32_16x16x4_f32 v[14:17], v184, v188, v[14:17]
	v_mfma_f32_16x16x4_f32 v[14:17], v185, v189, v[14:17]
	ds_read_b128 v[182:185], v21 offset:32
	s_waitcnt vmcnt(24) lgkmcnt(1)
	v_mfma_f32_16x16x4_f32 v[14:17], v218, v190, v[14:17]
	v_mfma_f32_16x16x4_f32 v[14:17], v219, v191, v[14:17]
	v_mfma_f32_16x16x4_f32 v[14:17], v220, v192, v[14:17]
	v_mfma_f32_16x16x4_f32 v[14:17], v221, v193, v[14:17]
	ds_read_b128 v[218:221], v21 offset:48
	s_waitcnt vmcnt(20) lgkmcnt(1)
	v_mfma_f32_16x16x4_f32 v[14:17], v182, v194, v[14:17]
	v_mfma_f32_16x16x4_f32 v[14:17], v183, v195, v[14:17]
	v_mfma_f32_16x16x4_f32 v[14:17], v184, v196, v[14:17]
	v_mfma_f32_16x16x4_f32 v[14:17], v185, v197, v[14:17]
	ds_read_b128 v[182:185], v21 offset:64
	s_waitcnt vmcnt(16) lgkmcnt(1)
	v_mfma_f32_16x16x4_f32 v[14:17], v218, v198, v[14:17]
	v_mfma_f32_16x16x4_f32 v[14:17], v219, v199, v[14:17]
	v_mfma_f32_16x16x4_f32 v[14:17], v220, v200, v[14:17]
	v_mfma_f32_16x16x4_f32 v[14:17], v221, v201, v[14:17]
	ds_read_b128 v[218:221], v21 offset:80
	s_waitcnt vmcnt(12) lgkmcnt(1)
	v_mfma_f32_16x16x4_f32 v[14:17], v182, v202, v[14:17]
	v_mfma_f32_16x16x4_f32 v[14:17], v183, v203, v[14:17]
	v_mfma_f32_16x16x4_f32 v[14:17], v184, v204, v[14:17]
	v_mfma_f32_16x16x4_f32 v[14:17], v185, v205, v[14:17]
	ds_read_b128 v[182:185], v21 offset:96
	s_waitcnt vmcnt(8) lgkmcnt(1)
	v_mfma_f32_16x16x4_f32 v[14:17], v218, v206, v[14:17]
	v_mfma_f32_16x16x4_f32 v[14:17], v219, v207, v[14:17]
	v_mfma_f32_16x16x4_f32 v[14:17], v220, v208, v[14:17]
	v_mfma_f32_16x16x4_f32 v[14:17], v221, v209, v[14:17]
	ds_read_b128 v[218:221], v21 offset:112
	s_waitcnt vmcnt(4) lgkmcnt(1)
	v_mfma_f32_16x16x4_f32 v[14:17], v182, v210, v[14:17]
	v_mfma_f32_16x16x4_f32 v[14:17], v183, v211, v[14:17]
	v_mfma_f32_16x16x4_f32 v[14:17], v184, v212, v[14:17]
	v_mfma_f32_16x16x4_f32 v[14:17], v185, v213, v[14:17]
	s_waitcnt vmcnt(0) lgkmcnt(0)
	v_mfma_f32_16x16x4_f32 v[14:17], v218, v214, v[14:17]
	v_mfma_f32_16x16x4_f32 v[14:17], v219, v215, v[14:17]
	v_mfma_f32_16x16x4_f32 v[14:17], v220, v216, v[14:17]
	v_mfma_f32_16x16x4_f32 v[14:17], v221, v217, v[14:17]
	s_nop 7
	s_nop 3
	v_mbcnt_lo_u32_b32 v20, -1, 0
	v_mbcnt_hi_u32_b32 v20, -1, v20
	v_lshrrev_b32_e32 v20, 4, v20
	v_lshl_add_u32 v20, v20, 8, v46
	ds_write_b32 v20, v14
	ds_write_b32 v20, v15 offset:64
	ds_write_b32 v20, v16 offset:128
	ds_write_b32 v20, v17 offset:192
	v_lshl_or_b32 v0, s2, 4, v35
	s_movk_i32 s3, 0xb32
	v_cmp_gt_i32_e32 vcc, s3, v0
	s_and_b64 s[14:15], s[6:7], vcc
	s_waitcnt lgkmcnt(0)
	s_barrier
	s_and_saveexec_b64 s[12:13], s[14:15]
	s_cbranch_execz .LBB0_1668
	ds_read2st64_b32 v[2:3], v41 offset1:4
	v_ashrrev_i32_e32 v1, 31, v0
	v_lshl_add_u64 v[0:1], v[0:1], 2, v[4:5]
	s_waitcnt lgkmcnt(0)
	v_add_f32_e32 v2, 0, v2
	v_add_f32_e32 v11, v2, v3
	ds_read2st64_b32 v[2:3], v41 offset0:8 offset1:12
	s_waitcnt lgkmcnt(0)
	v_add_f32_e32 v2, v11, v2
	v_add_f32_e32 v11, v2, v3
	ds_read2st64_b32 v[2:3], v41 offset0:16 offset1:20
	s_waitcnt lgkmcnt(0)
	v_add_f32_e32 v2, v11, v2
	v_add_f32_e32 v11, v2, v3
	ds_read2st64_b32 v[2:3], v41 offset0:24 offset1:28
	s_waitcnt lgkmcnt(0)
	v_add_f32_e32 v2, v11, v2
	v_add_f32_e32 v2, v2, v3
	ds_read_b32 v3, v42
	s_waitcnt lgkmcnt(0)
	v_mul_f32_e32 v2, v2, v3
	global_store_dword v[0:1], v2, off
	s_branch .LBB0_1668

; template <int M> DEVI float shx(float v) { return __int_as_float(__builtin_amdgcn_ds_swizzle(__float_as_int(v), (M << 10) | 0x1f)); }
; DEVI float shx32(float v, int lane) { return __int_as_float(__builtin_amdgcn_ds_bpermute((lane ^ 32) << 2, __float_as_int(v))); }
; DEVI void sk_gemm(const float* __restrict__ A, int lda, int K, const float* __restrict__ W, int N, const float* __restrict__ gain,
;                   bool use_rs, float* __restrict__ out, int ldo, int mode, unsigned char* lds, int wv, int bid, int nblk) {
;     ...
; #pragma unroll 2
;       for (int k = 0; k < ks; k += 4) {
;         const float w0 = Wp[(size_t)(k + 0) * N], w1 = Wp[(size_t)(k + 1) * N], w2 = Wp[(size_t)(k + 2) * N], w3 = Wp[(size_t)(k + 3) * N];
; #pragma unroll
;         for (int b = 0; b < 16; ++b) { const float4 a = *(const float4*)(Ap + b * 1024 + k); acc[b] += a.x * w0 + a.y * w1 + a.z * w2 + a.w * w3; }
;       }
;     }
; #pragma unroll
;     for (int b = 0; b < 16; ++b) { float v = acc[b]; v += shx<16>(v); v += shx32(v, lane); if (kq == 0) red[(wave * 16 + b) * 16 + c16] = v; }
;     __syncthreads();
;     if (tid < 256) {
;       const int b = tid >> 4, c = tid & 15; float v = 0.f;
; #pragma unroll
;       for (int w = 0; w < 8; ++w) v += red[(w * 16 + b) * 16 + c];
;       const int nn = grp * 16 + c;
;       if (nn < N) {
;         if (use_rs) v *= rsS[b];
;         float* o = out + (size_t)b * ldo + nn;
;         if (mode == 1) *o += v; else if (mode == 2) { v = fmaxf(v, 0.f); *o = v * v; } else *o = v;
.LBB0_1814:
	s_mov_b32 s16, 0xfffe4000
	s_mov_b32 s17, -1
	v_lshl_add_u64 v[18:19], v[12:13], 0, s[16:17]
	s_mov_b64 s[16:17], 0x4000
	global_load_dword v186, v[18:19], off
	v_lshl_add_u64 v[18:19], v[18:19], 0, s[16:17]
	global_load_dword v187, v[18:19], off
	v_lshl_add_u64 v[18:19], v[18:19], 0, s[16:17]
	global_load_dword v188, v[18:19], off
	v_lshl_add_u64 v[18:19], v[18:19], 0, s[16:17]
	global_load_dword v189, v[18:19], off
	v_lshl_add_u64 v[18:19], v[18:19], 0, s[16:17]
	global_load_dword v190, v[18:19], off
	v_lshl_add_u64 v[18:19], v[18:19], 0, s[16:17]
	global_load_dword v191, v[18:19], off
	v_lshl_add_u64 v[18:19], v[18:19], 0, s[16:17]
	global_load_dword v192, v[18:19], off
	v_lshl_add_u64 v[18:19], v[18:19], 0, s[16:17]
	global_load_dword v193, v[18:19], off
	v_lshl_add_u64 v[18:19], v[18:19], 0, s[16:17]
	global_load_dword v194, v[18:19], off
	v_lshl_add_u64 v[18:19], v[18:19], 0, s[16:17]
	global_load_dword v195, v[18:19], off
	v_lshl_add_u64 v[18:19], v[18:19], 0, s[16:17]
	global_load_dword v196, v[18:19], off
	v_lshl_add_u64 v[18:19], v[18:19], 0, s[16:17]
	global_load_dword v197, v[18:19], off
	v_lshl_add_u64 v[18:19], v[18:19], 0, s[16:17]
	global_load_dword v198, v[18:19], off
	v_lshl_add_u64 v[18:19], v[18:19], 0, s[16:17]
	global_load_dword v199, v[18:19], off
	v_lshl_add_u64 v[18:19], v[18:19], 0, s[16:17]
	global_load_dword v200, v[18:19], off
	v_lshl_add_u64 v[18:19], v[18:19], 0, s[16:17]
	global_load_dword v201, v[18:19], off
	v_lshl_add_u64 v[18:19], v[18:19], 0, s[16:17]
	global_load_dword v202, v[18:19], off
	v_lshl_add_u64 v[18:19], v[18:19], 0, s[16:17]
	global_load_dword v203, v[18:19], off
	v_lshl_add_u64 v[18:19], v[18:19], 0, s[16:17]
	global_load_dword v204, v[18:19], off
	v_lshl_add_u64 v[18:19], v[18:19], 0, s[16:17]
	global_load_dword v205, v[18:19], off
	v_lshl_add_u64 v[18:19], v[18:19], 0, s[16:17]
	global_load_dword v206, v[18:19], off
	v_lshl_add_u64 v[18:19], v[18:19], 0, s[16:17]
	global_load_dword v207, v[18:19], off
	v_lshl_add_u64 v[18:19], v[18:19], 0, s[16:17]
	global_load_dword v208, v[18:19], off
	v_lshl_add_u64 v[18:19], v[18:19], 0, s[16:17]
	global_load_dword v209, v[18:19], off
	v_lshl_add_u64 v[18:19], v[18:19], 0, s[16:17]
	global_load_dword v210, v[18:19], off
	v_lshl_add_u64 v[18:19], v[18:19], 0, s[16:17]
	global_load_dword v211, v[18:19], off
	v_lshl_add_u64 v[18:19], v[18:19], 0, s[16:17]
	global_load_dword v212, v[18:19], off
	v_lshl_add_u64 v[18:19], v[18:19], 0, s[16:17]
	global_load_dword v213, v[18:19], off
	v_lshl_add_u64 v[18:19], v[18:19], 0, s[16:17]
	global_load_dword v214, v[18:19], off
	v_lshl_add_u64 v[18:19], v[18:19], 0, s[16:17]
	global_load_dword v215, v[18:19], off
	v_lshl_add_u64 v[18:19], v[18:19], 0, s[16:17]
	global_load_dword v216, v[18:19], off
	v_lshl_add_u64 v[18:19], v[18:19], 0, s[16:17]
	global_load_dword v217, v[18:19], off
	v_mbcnt_lo_u32_b32 v20, -1, 0
	v_mbcnt_hi_u32_b32 v20, -1, v20
	v_and_b32_e32 v20, 15, v20
	v_lshl_add_u32 v21, v20, 12, v45
	ds_read_b128 v[182:185], v21
	ds_read_b128 v[218:221], v21 offset:16
	s_waitcnt vmcnt(28) lgkmcnt(1)
	v_mfma_f32_16x16x4_f32 v[14:17], v182, v186, v[14:17]
	v_mfma_f32_16x16x4_f32 v[14:17], v183, v187, v[14:17]
	v_mfma_f32_16x16x4_f32 v[14:17], v184, v188, v[14:17]
	v_mfma_f32_16x16x4_f32 v[14:17], v185, v189, v[14:17]
	ds_read_b128 v[182:185], v21 offset:32
	s_waitcnt vmcnt(24) lgkmcnt(1)
	v_mfma_f32_16x16x4_f32 v[14:17], v218, v190, v[14:17]
	v_mfma_f32_16x16x4_f32 v[14:17], v219, v191, v[14:17]
	v_mfma_f32_16x16x4_f32 v[14:17], v220, v192, v[14:17]
	v_mfma_f32_16x16x4_f32 v[14:17], v221, v193, v[14:17]
	ds_read_b128 v[218:221], v21 offset:48
	s_waitcnt vmcnt(20) lgkmcnt(1)
	v_mfma_f32_16x16x4_f32 v[14:17], v182, v194, v[14:17]
	v_mfma_f32_16x16x4_f32 v[14:17], v183, v195, v[14:17]
	v_mfma_f32_16x16x4_f32 v[14:17], v184, v196, v[14:17]
	v_mfma_f32_16x16x4_f32 v[14:17], v185, v197, v[14:17]
	ds_read_b128 v[182:185], v21 offset:64
	s_waitcnt vmcnt(16) lgkmcnt(1)
	v_mfma_f32_16x16x4_f32 v[14:17], v218, v198, v[14:17]
	v_mfma_f32_16x16x4_f32 v[14:17], v219, v199, v[14:17]
	v_mfma_f32_16x16x4_f32 v[14:17], v220, v200, v[14:17]
	v_mfma_f32_16x16x4_f32 v[14:17], v221, v201, v[14:17]
	ds_read_b128 v[218:221], v21 offset:80
	s_waitcnt vmcnt(12) lgkmcnt(1)
	v_mfma_f32_16x16x4_f32 v[14:17], v182, v202, v[14:17]
	v_mfma_f32_16x16x4_f32 v[14:17], v183, v203, v[14:17]
	v_mfma_f32_16x16x4_f32 v[14:17], v184, v204, v[14:17]
	v_mfma_f32_16x16x4_f32 v[14:17], v185, v205, v[14:17]
	ds_read_b128 v[182:185], v21 offset:96
	s_waitcnt vmcnt(8) lgkmcnt(1)
	v_mfma_f32_16x16x4_f32 v[14:17], v218, v206, v[14:17]
	v_mfma_f32_16x16x4_f32 v[14:17], v219, v207, v[14:17]
	v_mfma_f32_16x16x4_f32 v[14:17], v220, v208, v[14:17]
	v_mfma_f32_16x16x4_f32 v[14:17], v221, v209, v[14:17]
	ds_read_b128 v[218:221], v21 offset:112
	s_waitcnt vmcnt(4) lgkmcnt(1)
	v_mfma_f32_16x16x4_f32 v[14:17], v182, v210, v[14:17]
	v_mfma_f32_16x16x4_f32 v[14:17], v183, v211, v[14:17]
	v_mfma_f32_16x16x4_f32 v[14:17], v184, v212, v[14:17]
	v_mfma_f32_16x16x4_f32 v[14:17], v185, v213, v[14:17]
	s_waitcnt vmcnt(0) lgkmcnt(0)
	v_mfma_f32_16x16x4_f32 v[14:17], v218, v214, v[14:17]
	v_mfma_f32_16x16x4_f32 v[14:17], v219, v215, v[14:17]
	v_mfma_f32_16x16x4_f32 v[14:17], v220, v216, v[14:17]
	v_mfma_f32_16x16x4_f32 v[14:17], v221, v217, v[14:17]
	s_nop 7
	s_nop 3
	v_mbcnt_lo_u32_b32 v20, -1, 0
	v_mbcnt_hi_u32_b32 v20, -1, v20
	v_lshrrev_b32_e32 v20, 4, v20
	v_lshl_add_u32 v20, v20, 8, v46
	ds_write_b32 v20, v14
	ds_write_b32 v20, v15 offset:64
	ds_write_b32 v20, v16 offset:128
	ds_write_b32 v20, v17 offset:192
	v_lshl_or_b32 v0, s2, 4, v35
	s_movk_i32 s3, 0x1000
	v_cmp_gt_i32_e32 vcc, s3, v0
	s_and_b64 s[20:21], s[8:9], vcc
	s_waitcnt lgkmcnt(0)
	s_barrier
	s_and_saveexec_b64 s[16:17], s[20:21]
	s_cbranch_execz .LBB0_1808
	ds_read2st64_b32 v[2:3], v41 offset1:4
	s_waitcnt lgkmcnt(0)
	v_add_f32_e32 v1, 0, v2
	v_add_f32_e32 v1, v1, v3
	ds_read2st64_b32 v[2:3], v41 offset0:8 offset1:12
	s_waitcnt lgkmcnt(0)
	v_add_f32_e32 v1, v1, v2
	v_add_f32_e32 v1, v1, v3
	ds_read2st64_b32 v[2:3], v41 offset0:16 offset1:20
	s_waitcnt lgkmcnt(0)
	v_add_f32_e32 v1, v1, v2
	v_add_f32_e32 v1, v1, v3
	ds_read2st64_b32 v[2:3], v41 offset0:24 offset1:28
	s_waitcnt lgkmcnt(0)
	v_add_f32_e32 v1, v1, v2
	ds_read_b32 v2, v42
	v_add_f32_e32 v1, v1, v3
	s_waitcnt lgkmcnt(0)
	v_mul_f32_e32 v2, v1, v2
	v_ashrrev_i32_e32 v1, 31, v0
	v_max_f32_e32 v2, 0, v2
	v_lshl_add_u64 v[0:1], v[0:1], 2, v[4:5]
	v_mul_f32_e32 v2, v2, v2
	global_store_dword v[0:1], v2, off
	s_branch .LBB0_1808

; template <int M> DEVI float shx(float v) { return __int_as_float(__builtin_amdgcn_ds_swizzle(__float_as_int(v), (M << 10) | 0x1f)); }
; DEVI float shx32(float v, int lane) { return __int_as_float(__builtin_amdgcn_ds_bpermute((lane ^ 32) << 2, __float_as_int(v))); }
; DEVI void sk_gemm(const float* __restrict__ A, int lda, int K, const float* __restrict__ W, int N, const float* __restrict__ gain,
;                   bool use_rs, float* __restrict__ out, int ldo, int mode, unsigned char* lds, int wv, int bid, int nblk) {
;     ...
; #pragma unroll 2
;       for (int k = 0; k < ks; k += 4) {
;         const float w0 = Wp[(size_t)(k + 0) * N], w1 = Wp[(size_t)(k + 1) * N], w2 = Wp[(size_t)(k + 2) * N], w3 = Wp[(size_t)(k + 3) * N];
; #pragma unroll
;         for (int b = 0; b < 16; ++b) { const float4 a = *(const float4*)(Ap + b * 1024 + k); acc[b] += a.x * w0 + a.y * w1 + a.z * w2 + a.w * w3; }
;       }
;     }
; #pragma unroll
;     for (int b = 0; b < 16; ++b) { float v = acc[b]; v += shx<16>(v); v += shx32(v, lane); if (kq == 0) red[(wave * 16 + b) * 16 + c16] = v; }
;     __syncthreads();
;     if (tid < 256) {
;       const int b = tid >> 4, c = tid & 15; float v = 0.f;
; #pragma unroll
;       for (int w = 0; w < 8; ++w) v += red[(w * 16 + b) * 16 + c];
;       const int nn = grp * 16 + c;
;       if (nn < N) {
;         if (use_rs) v *= rsS[b];
;         float* o = out + (size_t)b * ldo + nn;
;         if (mode == 1) *o += v; else if (mode == 2) { v = fmaxf(v, 0.f); *o = v * v; } else *o = v;
.LBB0_1855:
	s_mov_b32 s8, 0xffff9000
	s_mov_b32 s9, -1
	v_lshl_add_u64 v[152:153], v[146:147], 0, s[8:9]
	s_mov_b64 s[8:9], 0x1000
	global_load_dword v186, v[152:153], off
	v_lshl_add_u64 v[152:153], v[152:153], 0, s[8:9]
	global_load_dword v187, v[152:153], off
	v_lshl_add_u64 v[152:153], v[152:153], 0, s[8:9]
	global_load_dword v188, v[152:153], off
	v_lshl_add_u64 v[152:153], v[152:153], 0, s[8:9]
	global_load_dword v189, v[152:153], off
	v_lshl_add_u64 v[152:153], v[152:153], 0, s[8:9]
	global_load_dword v190, v[152:153], off
	v_lshl_add_u64 v[152:153], v[152:153], 0, s[8:9]
	global_load_dword v191, v[152:153], off
	v_lshl_add_u64 v[152:153], v[152:153], 0, s[8:9]
	global_load_dword v192, v[152:153], off
	v_lshl_add_u64 v[152:153], v[152:153], 0, s[8:9]
	global_load_dword v193, v[152:153], off
	v_lshl_add_u64 v[152:153], v[152:153], 0, s[8:9]
	global_load_dword v194, v[152:153], off
	v_lshl_add_u64 v[152:153], v[152:153], 0, s[8:9]
	global_load_dword v195, v[152:153], off
	v_lshl_add_u64 v[152:153], v[152:153], 0, s[8:9]
	global_load_dword v196, v[152:153], off
	v_lshl_add_u64 v[152:153], v[152:153], 0, s[8:9]
	global_load_dword v197, v[152:153], off
	v_lshl_add_u64 v[152:153], v[152:153], 0, s[8:9]
	global_load_dword v198, v[152:153], off
	v_lshl_add_u64 v[152:153], v[152:153], 0, s[8:9]
	global_load_dword v199, v[152:153], off
	v_lshl_add_u64 v[152:153], v[152:153], 0, s[8:9]
	global_load_dword v200, v[152:153], off
	v_lshl_add_u64 v[152:153], v[152:153], 0, s[8:9]
	global_load_dword v201, v[152:153], off
	v_lshl_add_u64 v[152:153], v[152:153], 0, s[8:9]
	global_load_dword v202, v[152:153], off
	v_lshl_add_u64 v[152:153], v[152:153], 0, s[8:9]
	global_load_dword v203, v[152:153], off
	v_lshl_add_u64 v[152:153], v[152:153], 0, s[8:9]
	global_load_dword v204, v[152:153], off
	v_lshl_add_u64 v[152:153], v[152:153], 0, s[8:9]
	global_load_dword v205, v[152:153], off
	v_lshl_add_u64 v[152:153], v[152:153], 0, s[8:9]
	global_load_dword v206, v[152:153], off
	v_lshl_add_u64 v[152:153], v[152:153], 0, s[8:9]
	global_load_dword v207, v[152:153], off
	v_lshl_add_u64 v[152:153], v[152:153], 0, s[8:9]
	global_load_dword v208, v[152:153], off
	v_lshl_add_u64 v[152:153], v[152:153], 0, s[8:9]
	global_load_dword v209, v[152:153], off
	v_lshl_add_u64 v[152:153], v[152:153], 0, s[8:9]
	global_load_dword v210, v[152:153], off
	v_lshl_add_u64 v[152:153], v[152:153], 0, s[8:9]
	global_load_dword v211, v[152:153], off
	v_lshl_add_u64 v[152:153], v[152:153], 0, s[8:9]
	global_load_dword v212, v[152:153], off
	v_lshl_add_u64 v[152:153], v[152:153], 0, s[8:9]
	global_load_dword v213, v[152:153], off
	v_lshl_add_u64 v[152:153], v[152:153], 0, s[8:9]
	global_load_dword v214, v[152:153], off
	v_lshl_add_u64 v[152:153], v[152:153], 0, s[8:9]
	global_load_dword v215, v[152:153], off
	v_lshl_add_u64 v[152:153], v[152:153], 0, s[8:9]
	global_load_dword v216, v[152:153], off
	v_lshl_add_u64 v[152:153], v[152:153], 0, s[8:9]
	global_load_dword v217, v[152:153], off
	v_mbcnt_lo_u32_b32 v154, -1, 0
	v_mbcnt_hi_u32_b32 v154, -1, v154
	v_and_b32_e32 v154, 15, v154
	v_lshl_add_u32 v155, v154, 12, v172
	ds_read_b128 v[182:185], v155
	ds_read_b128 v[218:221], v155 offset:16
	s_waitcnt vmcnt(28) lgkmcnt(1)
	v_mfma_f32_16x16x4_f32 v[148:151], v182, v186, v[148:151]
	v_mfma_f32_16x16x4_f32 v[148:151], v183, v187, v[148:151]
	v_mfma_f32_16x16x4_f32 v[148:151], v184, v188, v[148:151]
	v_mfma_f32_16x16x4_f32 v[148:151], v185, v189, v[148:151]
	ds_read_b128 v[182:185], v155 offset:32
	s_waitcnt vmcnt(24) lgkmcnt(1)
	v_mfma_f32_16x16x4_f32 v[148:151], v218, v190, v[148:151]
	v_mfma_f32_16x16x4_f32 v[148:151], v219, v191, v[148:151]
	v_mfma_f32_16x16x4_f32 v[148:151], v220, v192, v[148:151]
	v_mfma_f32_16x16x4_f32 v[148:151], v221, v193, v[148:151]
	ds_read_b128 v[218:221], v155 offset:48
	s_waitcnt vmcnt(20) lgkmcnt(1)
	v_mfma_f32_16x16x4_f32 v[148:151], v182, v194, v[148:151]
	v_mfma_f32_16x16x4_f32 v[148:151], v183, v195, v[148:151]
	v_mfma_f32_16x16x4_f32 v[148:151], v184, v196, v[148:151]
	v_mfma_f32_16x16x4_f32 v[148:151], v185, v197, v[148:151]
	ds_read_b128 v[182:185], v155 offset:64
	s_waitcnt vmcnt(16) lgkmcnt(1)
	v_mfma_f32_16x16x4_f32 v[148:151], v218, v198, v[148:151]
	v_mfma_f32_16x16x4_f32 v[148:151], v219, v199, v[148:151]
	v_mfma_f32_16x16x4_f32 v[148:151], v220, v200, v[148:151]
	v_mfma_f32_16x16x4_f32 v[148:151], v221, v201, v[148:151]
	ds_read_b128 v[218:221], v155 offset:80
	s_waitcnt vmcnt(12) lgkmcnt(1)
	v_mfma_f32_16x16x4_f32 v[148:151], v182, v202, v[148:151]
	v_mfma_f32_16x16x4_f32 v[148:151], v183, v203, v[148:151]
	v_mfma_f32_16x16x4_f32 v[148:151], v184, v204, v[148:151]
	v_mfma_f32_16x16x4_f32 v[148:151], v185, v205, v[148:151]
	ds_read_b128 v[182:185], v155 offset:96
	s_waitcnt vmcnt(8) lgkmcnt(1)
	v_mfma_f32_16x16x4_f32 v[148:151], v218, v206, v[148:151]
	v_mfma_f32_16x16x4_f32 v[148:151], v219, v207, v[148:151]
	v_mfma_f32_16x16x4_f32 v[148:151], v220, v208, v[148:151]
	v_mfma_f32_16x16x4_f32 v[148:151], v221, v209, v[148:151]
	ds_read_b128 v[218:221], v155 offset:112
	s_waitcnt vmcnt(4) lgkmcnt(1)
	v_mfma_f32_16x16x4_f32 v[148:151], v182, v210, v[148:151]
	v_mfma_f32_16x16x4_f32 v[148:151], v183, v211, v[148:151]
	v_mfma_f32_16x16x4_f32 v[148:151], v184, v212, v[148:151]
	v_mfma_f32_16x16x4_f32 v[148:151], v185, v213, v[148:151]
	s_waitcnt vmcnt(0) lgkmcnt(0)
	v_mfma_f32_16x16x4_f32 v[148:151], v218, v214, v[148:151]
	v_mfma_f32_16x16x4_f32 v[148:151], v219, v215, v[148:151]
	v_mfma_f32_16x16x4_f32 v[148:151], v220, v216, v[148:151]
	v_mfma_f32_16x16x4_f32 v[148:151], v221, v217, v[148:151]
	s_nop 7
	s_nop 3
	v_mbcnt_lo_u32_b32 v154, -1, 0
	v_mbcnt_hi_u32_b32 v154, -1, v154
	v_lshrrev_b32_e32 v154, 4, v154
	v_lshl_add_u32 v154, v154, 8, v173
	ds_write_b32 v154, v148
	ds_write_b32 v154, v149 offset:64
	ds_write_b32 v154, v150 offset:128
	ds_write_b32 v154, v151 offset:192
	v_lshl_or_b32 v0, s2, 4, v131
	s_movk_i32 s3, 0x400
	v_cmp_gt_i32_e64 s[6:7], s3, v0
	s_and_b64 s[8:9], s[4:5], s[6:7]
	s_waitcnt lgkmcnt(0)
	s_barrier
	s_and_saveexec_b64 s[6:7], s[8:9]
	s_cbranch_execz .LBB0_1853
	ds_read2st64_b32 v[2:3], v170 offset1:4
	v_ashrrev_i32_e32 v1, 31, v0
	v_lshl_add_u64 v[0:1], v[0:1], 2, v[4:5]
	s_waitcnt lgkmcnt(0)
	v_add_f32_e32 v2, 0, v2
	v_add_f32_e32 v32, v2, v3
	ds_read2st64_b32 v[2:3], v170 offset0:8 offset1:12
	s_waitcnt lgkmcnt(0)
	v_add_f32_e32 v2, v32, v2
	v_add_f32_e32 v32, v2, v3
	ds_read2st64_b32 v[2:3], v170 offset0:16 offset1:20
	s_waitcnt lgkmcnt(0)
	v_add_f32_e32 v2, v32, v2
	v_add_f32_e32 v32, v2, v3
	ds_read2st64_b32 v[2:3], v170 offset0:24 offset1:28
	s_waitcnt lgkmcnt(0)
	v_add_f32_e32 v2, v32, v2
	v_add_f32_e32 v2, v2, v3
	global_load_dword v3, v[0:1], off
	s_waitcnt vmcnt(0)
	v_add_f32_e32 v2, v2, v3
	global_store_dword v[0:1], v2, off
	s_branch .LBB0_1853

; template <int M> DEVI float shx(float v) { return __int_as_float(__builtin_amdgcn_ds_swizzle(__float_as_int(v), (M << 10) | 0x1f)); }
; DEVI float shx32(float v, int lane) { return __int_as_float(__builtin_amdgcn_ds_bpermute((lane ^ 32) << 2, __float_as_int(v))); }
; DEVI void sk_gemm(const float* __restrict__ A, int lda, int K, const float* __restrict__ W, int N, const float* __restrict__ gain,
;                   bool use_rs, float* __restrict__ out, int ldo, int mode, unsigned char* lds, int wv, int bid, int nblk) {
;     ...
; #pragma unroll 2
;       for (int k = 0; k < ks; k += 4) {
;         const float w0 = Wp[(size_t)(k + 0) * N], w1 = Wp[(size_t)(k + 1) * N], w2 = Wp[(size_t)(k + 2) * N], w3 = Wp[(size_t)(k + 3) * N];
; #pragma unroll
;         for (int b = 0; b < 16; ++b) { const float4 a = *(const float4*)(Ap + b * 1024 + k); acc[b] += a.x * w0 + a.y * w1 + a.z * w2 + a.w * w3; }
;       }
;     }
; #pragma unroll
;     for (int b = 0; b < 16; ++b) { float v = acc[b]; v += shx<16>(v); v += shx32(v, lane); if (kq == 0) red[(wave * 16 + b) * 16 + c16] = v; }
;     __syncthreads();
;     if (tid < 256) {
;       const int b = tid >> 4, c = tid & 15; float v = 0.f;
; #pragma unroll
;       for (int w = 0; w < 8; ++w) v += red[(w * 16 + b) * 16 + c];
;       const int nn = grp * 16 + c;
;       if (nn < N) {
;         if (use_rs) v *= rsS[b];
;         float* o = out + (size_t)b * ldo + nn;
;         if (mode == 1) *o += v; else if (mode == 2) { v = fmaxf(v, 0.f); *o = v * v; } else *o = v;
.LBB0_1923:
	s_mov_b32 s18, 0xfffec688
	s_mov_b32 s19, -1
	v_lshl_add_u64 v[18:19], v[12:13], 0, s[18:19]
	s_mov_b64 s[18:19], 0x2cc8
	global_load_dword v186, v[18:19], off
	v_lshl_add_u64 v[18:19], v[18:19], 0, s[18:19]
	global_load_dword v187, v[18:19], off
	v_lshl_add_u64 v[18:19], v[18:19], 0, s[18:19]
	global_load_dword v188, v[18:19], off
	v_lshl_add_u64 v[18:19], v[18:19], 0, s[18:19]
	global_load_dword v189, v[18:19], off
	v_lshl_add_u64 v[18:19], v[18:19], 0, s[18:19]
	global_load_dword v190, v[18:19], off
	v_lshl_add_u64 v[18:19], v[18:19], 0, s[18:19]
	global_load_dword v191, v[18:19], off
	v_lshl_add_u64 v[18:19], v[18:19], 0, s[18:19]
	global_load_dword v192, v[18:19], off
	v_lshl_add_u64 v[18:19], v[18:19], 0, s[18:19]
	global_load_dword v193, v[18:19], off
	v_lshl_add_u64 v[18:19], v[18:19], 0, s[18:19]
	global_load_dword v194, v[18:19], off
	v_lshl_add_u64 v[18:19], v[18:19], 0, s[18:19]
	global_load_dword v195, v[18:19], off
	v_lshl_add_u64 v[18:19], v[18:19], 0, s[18:19]
	global_load_dword v196, v[18:19], off
	v_lshl_add_u64 v[18:19], v[18:19], 0, s[18:19]
	global_load_dword v197, v[18:19], off
	v_lshl_add_u64 v[18:19], v[18:19], 0, s[18:19]
	global_load_dword v198, v[18:19], off
	v_lshl_add_u64 v[18:19], v[18:19], 0, s[18:19]
	global_load_dword v199, v[18:19], off
	v_lshl_add_u64 v[18:19], v[18:19], 0, s[18:19]
	global_load_dword v200, v[18:19], off
	v_lshl_add_u64 v[18:19], v[18:19], 0, s[18:19]
	global_load_dword v201, v[18:19], off
	v_lshl_add_u64 v[18:19], v[18:19], 0, s[18:19]
	global_load_dword v202, v[18:19], off
	v_lshl_add_u64 v[18:19], v[18:19], 0, s[18:19]
	global_load_dword v203, v[18:19], off
	v_lshl_add_u64 v[18:19], v[18:19], 0, s[18:19]
	global_load_dword v204, v[18:19], off
	v_lshl_add_u64 v[18:19], v[18:19], 0, s[18:19]
	global_load_dword v205, v[18:19], off
	v_lshl_add_u64 v[18:19], v[18:19], 0, s[18:19]
	global_load_dword v206, v[18:19], off
	v_lshl_add_u64 v[18:19], v[18:19], 0, s[18:19]
	global_load_dword v207, v[18:19], off
	v_lshl_add_u64 v[18:19], v[18:19], 0, s[18:19]
	global_load_dword v208, v[18:19], off
	v_lshl_add_u64 v[18:19], v[18:19], 0, s[18:19]
	global_load_dword v209, v[18:19], off
	v_lshl_add_u64 v[18:19], v[18:19], 0, s[18:19]
	global_load_dword v210, v[18:19], off
	v_lshl_add_u64 v[18:19], v[18:19], 0, s[18:19]
	global_load_dword v211, v[18:19], off
	v_lshl_add_u64 v[18:19], v[18:19], 0, s[18:19]
	global_load_dword v212, v[18:19], off
	v_lshl_add_u64 v[18:19], v[18:19], 0, s[18:19]
	global_load_dword v213, v[18:19], off
	v_lshl_add_u64 v[18:19], v[18:19], 0, s[18:19]
	global_load_dword v214, v[18:19], off
	v_lshl_add_u64 v[18:19], v[18:19], 0, s[18:19]
	global_load_dword v215, v[18:19], off
	v_lshl_add_u64 v[18:19], v[18:19], 0, s[18:19]
	global_load_dword v216, v[18:19], off
	v_lshl_add_u64 v[18:19], v[18:19], 0, s[18:19]
	global_load_dword v217, v[18:19], off
	v_mbcnt_lo_u32_b32 v20, -1, 0
	v_mbcnt_hi_u32_b32 v20, -1, v20
	v_and_b32_e32 v20, 15, v20
	v_lshl_add_u32 v21, v20, 12, v45
	ds_read_b128 v[182:185], v21
	ds_read_b128 v[218:221], v21 offset:16
	s_waitcnt vmcnt(28) lgkmcnt(1)
	v_mfma_f32_16x16x4_f32 v[14:17], v182, v186, v[14:17]
	v_mfma_f32_16x16x4_f32 v[14:17], v183, v187, v[14:17]
	v_mfma_f32_16x16x4_f32 v[14:17], v184, v188, v[14:17]
	v_mfma_f32_16x16x4_f32 v[14:17], v185, v189, v[14:17]
	ds_read_b128 v[182:185], v21 offset:32
	s_waitcnt vmcnt(24) lgkmcnt(1)
	v_mfma_f32_16x16x4_f32 v[14:17], v218, v190, v[14:17]
	v_mfma_f32_16x16x4_f32 v[14:17], v219, v191, v[14:17]
	v_mfma_f32_16x16x4_f32 v[14:17], v220, v192, v[14:17]
	v_mfma_f32_16x16x4_f32 v[14:17], v221, v193, v[14:17]
	ds_read_b128 v[218:221], v21 offset:48
	s_waitcnt vmcnt(20) lgkmcnt(1)
	v_mfma_f32_16x16x4_f32 v[14:17], v182, v194, v[14:17]
	v_mfma_f32_16x16x4_f32 v[14:17], v183, v195, v[14:17]
	v_mfma_f32_16x16x4_f32 v[14:17], v184, v196, v[14:17]
	v_mfma_f32_16x16x4_f32 v[14:17], v185, v197, v[14:17]
	ds_read_b128 v[182:185], v21 offset:64
	s_waitcnt vmcnt(16) lgkmcnt(1)
	v_mfma_f32_16x16x4_f32 v[14:17], v218, v198, v[14:17]
	v_mfma_f32_16x16x4_f32 v[14:17], v219, v199, v[14:17]
	v_mfma_f32_16x16x4_f32 v[14:17], v220, v200, v[14:17]
	v_mfma_f32_16x16x4_f32 v[14:17], v221, v201, v[14:17]
	ds_read_b128 v[218:221], v21 offset:80
	s_waitcnt vmcnt(12) lgkmcnt(1)
	v_mfma_f32_16x16x4_f32 v[14:17], v182, v202, v[14:17]
	v_mfma_f32_16x16x4_f32 v[14:17], v183, v203, v[14:17]
	v_mfma_f32_16x16x4_f32 v[14:17], v184, v204, v[14:17]
	v_mfma_f32_16x16x4_f32 v[14:17], v185, v205, v[14:17]
	ds_read_b128 v[182:185], v21 offset:96
	s_waitcnt vmcnt(8) lgkmcnt(1)
	v_mfma_f32_16x16x4_f32 v[14:17], v218, v206, v[14:17]
	v_mfma_f32_16x16x4_f32 v[14:17], v219, v207, v[14:17]
	v_mfma_f32_16x16x4_f32 v[14:17], v220, v208, v[14:17]
	v_mfma_f32_16x16x4_f32 v[14:17], v221, v209, v[14:17]
	ds_read_b128 v[218:221], v21 offset:112
	s_waitcnt vmcnt(4) lgkmcnt(1)
	v_mfma_f32_16x16x4_f32 v[14:17], v182, v210, v[14:17]
	v_mfma_f32_16x16x4_f32 v[14:17], v183, v211, v[14:17]
	v_mfma_f32_16x16x4_f32 v[14:17], v184, v212, v[14:17]
	v_mfma_f32_16x16x4_f32 v[14:17], v185, v213, v[14:17]
	s_waitcnt vmcnt(0) lgkmcnt(0)
	v_mfma_f32_16x16x4_f32 v[14:17], v218, v214, v[14:17]
	v_mfma_f32_16x16x4_f32 v[14:17], v219, v215, v[14:17]
	v_mfma_f32_16x16x4_f32 v[14:17], v220, v216, v[14:17]
	v_mfma_f32_16x16x4_f32 v[14:17], v221, v217, v[14:17]
	s_nop 7
	s_nop 3
	v_mbcnt_lo_u32_b32 v20, -1, 0
	v_mbcnt_hi_u32_b32 v20, -1, v20
	v_lshrrev_b32_e32 v20, 4, v20
	v_lshl_add_u32 v20, v20, 8, v46
	ds_write_b32 v20, v14
	ds_write_b32 v20, v15 offset:64
	ds_write_b32 v20, v16 offset:128
	ds_write_b32 v20, v17 offset:192
	v_lshl_or_b32 v0, s2, 4, v35
	s_movk_i32 s3, 0xb32
	v_cmp_gt_i32_e32 vcc, s3, v0
	s_and_b64 s[16:17], s[8:9], vcc
	s_waitcnt lgkmcnt(0)
	s_barrier
	s_and_saveexec_b64 s[14:15], s[16:17]
	s_cbranch_execz .LBB0_1917
	ds_read2st64_b32 v[2:3], v41 offset1:4
	v_ashrrev_i32_e32 v1, 31, v0
	v_lshl_add_u64 v[0:1], v[0:1], 2, v[4:5]
	s_waitcnt lgkmcnt(0)
	v_add_f32_e32 v2, 0, v2
	v_add_f32_e32 v11, v2, v3
	ds_read2st64_b32 v[2:3], v41 offset0:8 offset1:12
	s_waitcnt lgkmcnt(0)
	v_add_f32_e32 v2, v11, v2
	v_add_f32_e32 v11, v2, v3
	ds_read2st64_b32 v[2:3], v41 offset0:16 offset1:20
	s_waitcnt lgkmcnt(0)
	v_add_f32_e32 v2, v11, v2
	v_add_f32_e32 v11, v2, v3
	ds_read2st64_b32 v[2:3], v41 offset0:24 offset1:28
	s_waitcnt lgkmcnt(0)
	v_add_f32_e32 v2, v11, v2
	v_add_f32_e32 v2, v2, v3
	ds_read_b32 v3, v42
	s_waitcnt lgkmcnt(0)
	v_mul_f32_e32 v2, v2, v3
	global_store_dword v[0:1], v2, off
	s_branch .LBB0_1917

; template <int M> DEVI float shx(float v) { return __int_as_float(__builtin_amdgcn_ds_swizzle(__float_as_int(v), (M << 10) | 0x1f)); }
; DEVI float shx32(float v, int lane) { return __int_as_float(__builtin_amdgcn_ds_bpermute((lane ^ 32) << 2, __float_as_int(v))); }
; DEVI void sk_gemm(const float* __restrict__ A, int lda, int K, const float* __restrict__ W, int N, const float* __restrict__ gain,
;                   bool use_rs, float* __restrict__ out, int ldo, int mode, unsigned char* lds, int wv, int bid, int nblk) {
;     ...
; #pragma unroll 2
;       for (int k = 0; k < ks; k += 4) {
;         const float w0 = Wp[(size_t)(k + 0) * N], w1 = Wp[(size_t)(k + 1) * N], w2 = Wp[(size_t)(k + 2) * N], w3 = Wp[(size_t)(k + 3) * N];
; #pragma unroll
;         for (int b = 0; b < 16; ++b) { const float4 a = *(const float4*)(Ap + b * 1024 + k); acc[b] += a.x * w0 + a.y * w1 + a.z * w2 + a.w * w3; }
;       }
;     }
; #pragma unroll
;     for (int b = 0; b < 16; ++b) { float v = acc[b]; v += shx<16>(v); v += shx32(v, lane); if (kq == 0) red[(wave * 16 + b) * 16 + c16] = v; }
;     __syncthreads();
;     if (tid < 256) {
;       const int b = tid >> 4, c = tid & 15; float v = 0.f;
; #pragma unroll
;       for (int w = 0; w < 8; ++w) v += red[(w * 16 + b) * 16 + c];
;       const int nn = grp * 16 + c;
;       if (nn < N) {
;         if (use_rs) v *= rsS[b];
;         float* o = out + (size_t)b * ldo + nn;
;         if (mode == 1) *o += v; else if (mode == 2) { v = fmaxf(v, 0.f); *o = v * v; } else *o = v;
.LBB0_2156:
	s_mov_b32 s14, 0xfffec688
	s_mov_b32 s15, -1
	v_lshl_add_u64 v[18:19], v[12:13], 0, s[14:15]
	s_mov_b64 s[14:15], 0x2cc8
	global_load_dword v186, v[18:19], off
	v_lshl_add_u64 v[18:19], v[18:19], 0, s[14:15]
	global_load_dword v187, v[18:19], off
	v_lshl_add_u64 v[18:19], v[18:19], 0, s[14:15]
	global_load_dword v188, v[18:19], off
	v_lshl_add_u64 v[18:19], v[18:19], 0, s[14:15]
	global_load_dword v189, v[18:19], off
	v_lshl_add_u64 v[18:19], v[18:19], 0, s[14:15]
	global_load_dword v190, v[18:19], off
	v_lshl_add_u64 v[18:19], v[18:19], 0, s[14:15]
	global_load_dword v191, v[18:19], off
	v_lshl_add_u64 v[18:19], v[18:19], 0, s[14:15]
	global_load_dword v192, v[18:19], off
	v_lshl_add_u64 v[18:19], v[18:19], 0, s[14:15]
	global_load_dword v193, v[18:19], off
	v_lshl_add_u64 v[18:19], v[18:19], 0, s[14:15]
	global_load_dword v194, v[18:19], off
	v_lshl_add_u64 v[18:19], v[18:19], 0, s[14:15]
	global_load_dword v195, v[18:19], off
	v_lshl_add_u64 v[18:19], v[18:19], 0, s[14:15]
	global_load_dword v196, v[18:19], off
	v_lshl_add_u64 v[18:19], v[18:19], 0, s[14:15]
	global_load_dword v197, v[18:19], off
	v_lshl_add_u64 v[18:19], v[18:19], 0, s[14:15]
	global_load_dword v198, v[18:19], off
	v_lshl_add_u64 v[18:19], v[18:19], 0, s[14:15]
	global_load_dword v199, v[18:19], off
	v_lshl_add_u64 v[18:19], v[18:19], 0, s[14:15]
	global_load_dword v200, v[18:19], off
	v_lshl_add_u64 v[18:19], v[18:19], 0, s[14:15]
	global_load_dword v201, v[18:19], off
	v_lshl_add_u64 v[18:19], v[18:19], 0, s[14:15]
	global_load_dword v202, v[18:19], off
	v_lshl_add_u64 v[18:19], v[18:19], 0, s[14:15]
	global_load_dword v203, v[18:19], off
	v_lshl_add_u64 v[18:19], v[18:19], 0, s[14:15]
	global_load_dword v204, v[18:19], off
	v_lshl_add_u64 v[18:19], v[18:19], 0, s[14:15]
	global_load_dword v205, v[18:19], off
	v_lshl_add_u64 v[18:19], v[18:19], 0, s[14:15]
	global_load_dword v206, v[18:19], off
	v_lshl_add_u64 v[18:19], v[18:19], 0, s[14:15]
	global_load_dword v207, v[18:19], off
	v_lshl_add_u64 v[18:19], v[18:19], 0, s[14:15]
	global_load_dword v208, v[18:19], off
	v_lshl_add_u64 v[18:19], v[18:19], 0, s[14:15]
	global_load_dword v209, v[18:19], off
	v_lshl_add_u64 v[18:19], v[18:19], 0, s[14:15]
	global_load_dword v210, v[18:19], off
	v_lshl_add_u64 v[18:19], v[18:19], 0, s[14:15]
	global_load_dword v211, v[18:19], off
	v_lshl_add_u64 v[18:19], v[18:19], 0, s[14:15]
	global_load_dword v212, v[18:19], off
	v_lshl_add_u64 v[18:19], v[18:19], 0, s[14:15]
	global_load_dword v213, v[18:19], off
	v_lshl_add_u64 v[18:19], v[18:19], 0, s[14:15]
	global_load_dword v214, v[18:19], off
	v_lshl_add_u64 v[18:19], v[18:19], 0, s[14:15]
	global_load_dword v215, v[18:19], off
	v_lshl_add_u64 v[18:19], v[18:19], 0, s[14:15]
	global_load_dword v216, v[18:19], off
	v_lshl_add_u64 v[18:19], v[18:19], 0, s[14:15]
	global_load_dword v217, v[18:19], off
	v_mbcnt_lo_u32_b32 v20, -1, 0
	v_mbcnt_hi_u32_b32 v20, -1, v20
	v_and_b32_e32 v20, 15, v20
	v_lshl_add_u32 v21, v20, 12, v45
	ds_read_b128 v[182:185], v21
	ds_read_b128 v[218:221], v21 offset:16
	s_waitcnt vmcnt(28) lgkmcnt(1)
	v_mfma_f32_16x16x4_f32 v[14:17], v182, v186, v[14:17]
	v_mfma_f32_16x16x4_f32 v[14:17], v183, v187, v[14:17]
	v_mfma_f32_16x16x4_f32 v[14:17], v184, v188, v[14:17]
	v_mfma_f32_16x16x4_f32 v[14:17], v185, v189, v[14:17]
	ds_read_b128 v[182:185], v21 offset:32
	s_waitcnt vmcnt(24) lgkmcnt(1)
	v_mfma_f32_16x16x4_f32 v[14:17], v218, v190, v[14:17]
	v_mfma_f32_16x16x4_f32 v[14:17], v219, v191, v[14:17]
	v_mfma_f32_16x16x4_f32 v[14:17], v220, v192, v[14:17]
	v_mfma_f32_16x16x4_f32 v[14:17], v221, v193, v[14:17]
	ds_read_b128 v[218:221], v21 offset:48
	s_waitcnt vmcnt(20) lgkmcnt(1)
	v_mfma_f32_16x16x4_f32 v[14:17], v182, v194, v[14:17]
	v_mfma_f32_16x16x4_f32 v[14:17], v183, v195, v[14:17]
	v_mfma_f32_16x16x4_f32 v[14:17], v184, v196, v[14:17]
	v_mfma_f32_16x16x4_f32 v[14:17], v185, v197, v[14:17]
	ds_read_b128 v[182:185], v21 offset:64
	s_waitcnt vmcnt(16) lgkmcnt(1)
	v_mfma_f32_16x16x4_f32 v[14:17], v218, v198, v[14:17]
	v_mfma_f32_16x16x4_f32 v[14:17], v219, v199, v[14:17]
	v_mfma_f32_16x16x4_f32 v[14:17], v220, v200, v[14:17]
	v_mfma_f32_16x16x4_f32 v[14:17], v221, v201, v[14:17]
	ds_read_b128 v[218:221], v21 offset:80
	s_waitcnt vmcnt(12) lgkmcnt(1)
	v_mfma_f32_16x16x4_f32 v[14:17], v182, v202, v[14:17]
	v_mfma_f32_16x16x4_f32 v[14:17], v183, v203, v[14:17]
	v_mfma_f32_16x16x4_f32 v[14:17], v184, v204, v[14:17]
	v_mfma_f32_16x16x4_f32 v[14:17], v185, v205, v[14:17]
	ds_read_b128 v[182:185], v21 offset:96
	s_waitcnt vmcnt(8) lgkmcnt(1)
	v_mfma_f32_16x16x4_f32 v[14:17], v218, v206, v[14:17]
	v_mfma_f32_16x16x4_f32 v[14:17], v219, v207, v[14:17]
	v_mfma_f32_16x16x4_f32 v[14:17], v220, v208, v[14:17]
	v_mfma_f32_16x16x4_f32 v[14:17], v221, v209, v[14:17]
	ds_read_b128 v[218:221], v21 offset:112
	s_waitcnt vmcnt(4) lgkmcnt(1)
	v_mfma_f32_16x16x4_f32 v[14:17], v182, v210, v[14:17]
	v_mfma_f32_16x16x4_f32 v[14:17], v183, v211, v[14:17]
	v_mfma_f32_16x16x4_f32 v[14:17], v184, v212, v[14:17]
	v_mfma_f32_16x16x4_f32 v[14:17], v185, v213, v[14:17]
	s_waitcnt vmcnt(0) lgkmcnt(0)
	v_mfma_f32_16x16x4_f32 v[14:17], v218, v214, v[14:17]
	v_mfma_f32_16x16x4_f32 v[14:17], v219, v215, v[14:17]
	v_mfma_f32_16x16x4_f32 v[14:17], v220, v216, v[14:17]
	v_mfma_f32_16x16x4_f32 v[14:17], v221, v217, v[14:17]
	s_nop 7
	s_nop 3
	v_mbcnt_lo_u32_b32 v20, -1, 0
	v_mbcnt_hi_u32_b32 v20, -1, v20
	v_lshrrev_b32_e32 v20, 4, v20
	v_lshl_add_u32 v20, v20, 8, v46
	ds_write_b32 v20, v14
	ds_write_b32 v20, v15 offset:64
	ds_write_b32 v20, v16 offset:128
	ds_write_b32 v20, v17 offset:192
	v_lshl_or_b32 v0, s2, 4, v35
	s_movk_i32 s3, 0xb32
	v_cmp_gt_i32_e32 vcc, s3, v0
	s_and_b64 s[16:17], s[8:9], vcc
	s_waitcnt lgkmcnt(0)
	s_barrier
	s_and_saveexec_b64 s[14:15], s[16:17]
	s_cbranch_execz .LBB0_2150
	ds_read2st64_b32 v[2:3], v41 offset1:4
	v_ashrrev_i32_e32 v1, 31, v0
	v_lshl_add_u64 v[0:1], v[0:1], 2, v[4:5]
	s_waitcnt lgkmcnt(0)
	v_add_f32_e32 v2, 0, v2
	v_add_f32_e32 v11, v2, v3
	ds_read2st64_b32 v[2:3], v41 offset0:8 offset1:12
	s_waitcnt lgkmcnt(0)
	v_add_f32_e32 v2, v11, v2
	v_add_f32_e32 v11, v2, v3
	ds_read2st64_b32 v[2:3], v41 offset0:16 offset1:20
	s_waitcnt lgkmcnt(0)
	v_add_f32_e32 v2, v11, v2
	v_add_f32_e32 v11, v2, v3
	ds_read2st64_b32 v[2:3], v41 offset0:24 offset1:28
	s_waitcnt lgkmcnt(0)
	v_add_f32_e32 v2, v11, v2
	v_add_f32_e32 v2, v2, v3
	ds_read_b32 v3, v42
	s_waitcnt lgkmcnt(0)
	v_mul_f32_e32 v2, v2, v3
	global_store_dword v[0:1], v2, off
	s_branch .LBB0_2150
